# back-edge rotation (asm guide 7.11): K-loop counter / pointer updates and exit compare moved in front of the loop-back barrier in nine K loops
# baseline (speedup 1.0000x reference)
.LBB0_181:
	ds_read_b128 v[128:131], v173
	ds_read_b128 v[132:135], v173 offset:1024
	ds_read_b128 v[136:139], v173 offset:2048
	ds_read_b128 v[140:143], v173 offset:3072
	ds_read_b128 v[162:165], v174
	ds_read_b128 v[166:169], v174 offset:1024
	ds_read_b128 v[176:179], v174 offset:2048
	ds_read_b128 v[180:183], v174 offset:3072
	s_add_u32 s6, s4, 0xfff80080
	s_addc_u32 s7, s5, -1
	s_cmp_eq_u32 s96, 28
	s_cselect_b32 s9, s26, s7
	s_cselect_b32 s8, s27, s6
	s_cselect_b32 s7, s86, s95
	s_cselect_b32 s6, s91, s94
	v_lshl_add_u64 v[216:217], s[4:5], 0, v[158:159]
	s_add_i32 m0, s47, 0xc000
	ds_read_b128 v[184:187], v175
	ds_read_b128 v[188:191], v175 offset:1024
	ds_read_b128 v[192:195], v175 offset:2048
	ds_read_b128 v[196:199], v175 offset:3072
	ds_read_b128 v[200:203], v175 offset:4096
	ds_read_b128 v[204:207], v175 offset:5120
	ds_read_b128 v[208:211], v175 offset:6144
	ds_read_b128 v[212:215], v175 offset:7168
	global_load_lds_dwordx4 v[216:217], off
	v_lshl_add_u64 v[216:217], s[4:5], 0, v[160:161]
	s_add_i32 m0, s47, 0xe000
	s_nop 0
	global_load_lds_dwordx4 v[216:217], off
	s_waitcnt vmcnt(8)
	s_waitcnt lgkmcnt(0)
	s_barrier
	s_setprio 1
	s_waitcnt lgkmcnt(0)
	v_mfma_f32_16x16x32_bf16 v[124:127], v[128:131], v[184:187], v[124:127]
	v_mfma_f32_16x16x32_bf16 v[120:123], v[136:139], v[184:187], v[120:123]
	v_mfma_f32_16x16x32_bf16 v[108:111], v[128:131], v[192:195], v[108:111]
	v_mfma_f32_16x16x32_bf16 v[104:107], v[136:139], v[192:195], v[104:107]
	v_mfma_f32_16x16x32_bf16 v[92:95], v[128:131], v[200:203], v[92:95]
	v_mfma_f32_16x16x32_bf16 v[88:91], v[136:139], v[200:203], v[88:91]
	v_mfma_f32_16x16x32_bf16 v[76:79], v[128:131], v[208:211], v[76:79]
	v_mfma_f32_16x16x32_bf16 v[72:75], v[136:139], v[208:211], v[72:75]
	v_mfma_f32_16x16x32_bf16 v[124:127], v[132:135], v[188:191], v[124:127]
	v_mfma_f32_16x16x32_bf16 v[120:123], v[140:143], v[188:191], v[120:123]
	v_mfma_f32_16x16x32_bf16 v[108:111], v[132:135], v[196:199], v[108:111]
	v_mfma_f32_16x16x32_bf16 v[104:107], v[140:143], v[196:199], v[104:107]
	v_mfma_f32_16x16x32_bf16 v[92:95], v[132:135], v[204:207], v[92:95]
	v_mfma_f32_16x16x32_bf16 v[88:91], v[140:143], v[204:207], v[88:91]
	v_mfma_f32_16x16x32_bf16 v[76:79], v[132:135], v[212:215], v[76:79]
	v_mfma_f32_16x16x32_bf16 v[72:75], v[140:143], v[212:215], v[72:75]
	s_setprio 0
	s_setprio 1
	v_mfma_f32_16x16x32_bf16 v[116:119], v[162:165], v[184:187], v[116:119]
	v_mfma_f32_16x16x32_bf16 v[112:115], v[176:179], v[184:187], v[112:115]
	v_mfma_f32_16x16x32_bf16 v[100:103], v[162:165], v[192:195], v[100:103]
	v_mfma_f32_16x16x32_bf16 v[96:99], v[176:179], v[192:195], v[96:99]
	v_mfma_f32_16x16x32_bf16 v[84:87], v[162:165], v[200:203], v[84:87]
	v_mfma_f32_16x16x32_bf16 v[80:83], v[176:179], v[200:203], v[80:83]
	v_mfma_f32_16x16x32_bf16 v[68:71], v[162:165], v[208:211], v[68:71]
	v_mfma_f32_16x16x32_bf16 v[64:67], v[176:179], v[208:211], v[64:67]
	v_mfma_f32_16x16x32_bf16 v[116:119], v[166:169], v[188:191], v[116:119]
	v_mfma_f32_16x16x32_bf16 v[112:115], v[180:183], v[188:191], v[112:115]
	v_mfma_f32_16x16x32_bf16 v[100:103], v[166:169], v[196:199], v[100:103]
	v_mfma_f32_16x16x32_bf16 v[96:99], v[180:183], v[196:199], v[96:99]
	v_mfma_f32_16x16x32_bf16 v[84:87], v[166:169], v[204:207], v[84:87]
	v_mfma_f32_16x16x32_bf16 v[80:83], v[180:183], v[204:207], v[80:83]
	v_mfma_f32_16x16x32_bf16 v[68:71], v[166:169], v[212:215], v[68:71]
	v_mfma_f32_16x16x32_bf16 v[64:67], v[180:183], v[212:215], v[64:67]
	s_setprio 0
	s_barrier
	s_add_i32 s97, s30, s44
	v_lshl_add_u64 v[216:217], s[6:7], 0, v[146:147]
	s_mov_b32 m0, s97
	ds_read_b128 v[184:187], v175 offset:16384
	ds_read_b128 v[188:191], v175 offset:17408
	ds_read_b128 v[192:195], v175 offset:18432
	ds_read_b128 v[196:199], v175 offset:19456
	ds_read_b128 v[200:203], v175 offset:20480
	ds_read_b128 v[204:207], v175 offset:21504
	ds_read_b128 v[208:211], v175 offset:22528
	ds_read_b128 v[212:215], v175 offset:23552
	global_load_lds_dwordx4 v[216:217], off
	s_add_i32 m0, s97, 0x2000
	s_add_u32 vcc_lo, s6, 0x80000
	v_lshl_add_u64 v[218:219], s[6:7], 0, v[144:145]
	s_addc_u32 vcc_hi, s7, 0
	s_add_i32 s97, s31, s44
	global_load_lds_dwordx4 v[218:219], off
	v_lshl_add_u64 v[220:221], vcc, 0, v[146:147]
	s_mov_b32 m0, s97
	v_lshl_add_u64 v[222:223], s[8:9], 0, v[144:145]
	global_load_lds_dwordx4 v[220:221], off
	v_lshl_add_u64 v[220:221], vcc, 0, v[144:145]
	s_add_i32 m0, s97, 0x2000
	s_nop 0
	global_load_lds_dwordx4 v[220:221], off
	v_lshl_add_u64 v[220:221], s[8:9], 0, v[146:147]
	s_mov_b32 m0, s47
	s_nop 0
	global_load_lds_dwordx4 v[220:221], off
	s_mov_b32 m0, s48
	s_nop 0
	global_load_lds_dwordx4 v[222:223], off
	s_waitcnt vmcnt(8)
	s_waitcnt lgkmcnt(0)
	s_barrier
	s_setprio 1
	s_waitcnt lgkmcnt(0)
	v_mfma_f32_16x16x32_bf16 v[60:63], v[128:131], v[184:187], v[60:63]
	v_mfma_f32_16x16x32_bf16 v[56:59], v[136:139], v[184:187], v[56:59]
	v_mfma_f32_16x16x32_bf16 v[44:47], v[128:131], v[192:195], v[44:47]
	v_mfma_f32_16x16x32_bf16 v[40:43], v[136:139], v[192:195], v[40:43]
	v_mfma_f32_16x16x32_bf16 v[28:31], v[128:131], v[200:203], v[28:31]
	v_mfma_f32_16x16x32_bf16 v[24:27], v[136:139], v[200:203], v[24:27]
	v_mfma_f32_16x16x32_bf16 v[12:15], v[128:131], v[208:211], v[12:15]
	v_mfma_f32_16x16x32_bf16 v[8:11], v[136:139], v[208:211], v[8:11]
	v_mfma_f32_16x16x32_bf16 v[60:63], v[132:135], v[188:191], v[60:63]
	v_mfma_f32_16x16x32_bf16 v[56:59], v[140:143], v[188:191], v[56:59]
	v_mfma_f32_16x16x32_bf16 v[44:47], v[132:135], v[196:199], v[44:47]
	v_mfma_f32_16x16x32_bf16 v[40:43], v[140:143], v[196:199], v[40:43]
	v_mfma_f32_16x16x32_bf16 v[28:31], v[132:135], v[204:207], v[28:31]
	v_mfma_f32_16x16x32_bf16 v[24:27], v[140:143], v[204:207], v[24:27]
	v_mfma_f32_16x16x32_bf16 v[12:15], v[132:135], v[212:215], v[12:15]
	v_mfma_f32_16x16x32_bf16 v[8:11], v[140:143], v[212:215], v[8:11]
	s_setprio 0
	s_setprio 1
	v_mfma_f32_16x16x32_bf16 v[52:55], v[162:165], v[184:187], v[52:55]
	v_mfma_f32_16x16x32_bf16 v[48:51], v[176:179], v[184:187], v[48:51]
	v_mfma_f32_16x16x32_bf16 v[36:39], v[162:165], v[192:195], v[36:39]
	v_mfma_f32_16x16x32_bf16 v[32:35], v[176:179], v[192:195], v[32:35]
	v_mfma_f32_16x16x32_bf16 v[20:23], v[162:165], v[200:203], v[20:23]
	v_mfma_f32_16x16x32_bf16 v[16:19], v[176:179], v[200:203], v[16:19]
	v_mfma_f32_16x16x32_bf16 v[4:7], v[162:165], v[208:211], v[4:7]
	v_mfma_f32_16x16x32_bf16 v[0:3], v[176:179], v[208:211], v[0:3]
	v_mfma_f32_16x16x32_bf16 v[52:55], v[166:169], v[188:191], v[52:55]
	v_mfma_f32_16x16x32_bf16 v[48:51], v[180:183], v[188:191], v[48:51]
	v_mfma_f32_16x16x32_bf16 v[36:39], v[166:169], v[196:199], v[36:39]
	v_mfma_f32_16x16x32_bf16 v[32:35], v[180:183], v[196:199], v[32:35]
	v_mfma_f32_16x16x32_bf16 v[20:23], v[166:169], v[204:207], v[20:23]
	v_mfma_f32_16x16x32_bf16 v[16:19], v[180:183], v[204:207], v[16:19]
	v_mfma_f32_16x16x32_bf16 v[4:7], v[166:169], v[212:215], v[4:7]
	v_mfma_f32_16x16x32_bf16 v[0:3], v[180:183], v[212:215], v[0:3]
	s_setprio 0
	s_barrier
	s_add_i32 s97, 0, 0x18000
	s_add_i32 vcc_lo, 0, 0x1c000
	v_add_u32_e32 v140, s97, v153
	v_add_u32_e32 v180, vcc_lo, v153
	ds_read_b128 v[128:131], v140
	ds_read_b128 v[132:135], v140 offset:1024
	ds_read_b128 v[136:139], v140 offset:2048
	ds_read_b128 v[140:143], v140 offset:3072
	ds_read_b128 v[162:165], v180
	ds_read_b128 v[166:169], v180 offset:1024
	ds_read_b128 v[176:179], v180 offset:2048
	ds_read_b128 v[180:183], v180 offset:3072
	s_add_u32 s8, s8, 0x80000
	s_addc_u32 s9, s9, 0
	s_mov_b32 m0, s49
	v_lshl_add_u64 v[224:225], s[8:9], 0, v[146:147]
	ds_read_b128 v[184:187], v175 offset:32768
	ds_read_b128 v[188:191], v175 offset:33792
	ds_read_b128 v[192:195], v175 offset:34816
	ds_read_b128 v[196:199], v175 offset:35840
	ds_read_b128 v[200:203], v175 offset:36864
	ds_read_b128 v[204:207], v175 offset:37888
	ds_read_b128 v[208:211], v175 offset:38912
	ds_read_b128 v[212:215], v175 offset:39936
	global_load_lds_dwordx4 v[224:225], off
	v_lshl_add_u64 v[224:225], s[8:9], 0, v[144:145]
	s_mov_b32 m0, s50
	s_nop 0
	global_load_lds_dwordx4 v[224:225], off
	s_waitcnt vmcnt(8)
	s_waitcnt lgkmcnt(0)
	s_barrier
	s_setprio 1
	s_waitcnt lgkmcnt(0)
	v_mfma_f32_16x16x32_bf16 v[124:127], v[128:131], v[184:187], v[124:127]
	v_mfma_f32_16x16x32_bf16 v[120:123], v[136:139], v[184:187], v[120:123]
	v_mfma_f32_16x16x32_bf16 v[108:111], v[128:131], v[192:195], v[108:111]
	v_mfma_f32_16x16x32_bf16 v[104:107], v[136:139], v[192:195], v[104:107]
	v_mfma_f32_16x16x32_bf16 v[92:95], v[128:131], v[200:203], v[92:95]
	v_mfma_f32_16x16x32_bf16 v[88:91], v[136:139], v[200:203], v[88:91]
	v_mfma_f32_16x16x32_bf16 v[76:79], v[128:131], v[208:211], v[76:79]
	v_mfma_f32_16x16x32_bf16 v[72:75], v[136:139], v[208:211], v[72:75]
	v_mfma_f32_16x16x32_bf16 v[124:127], v[132:135], v[188:191], v[124:127]
	v_mfma_f32_16x16x32_bf16 v[120:123], v[140:143], v[188:191], v[120:123]
	v_mfma_f32_16x16x32_bf16 v[108:111], v[132:135], v[196:199], v[108:111]
	v_mfma_f32_16x16x32_bf16 v[104:107], v[140:143], v[196:199], v[104:107]
	v_mfma_f32_16x16x32_bf16 v[92:95], v[132:135], v[204:207], v[92:95]
	v_mfma_f32_16x16x32_bf16 v[88:91], v[140:143], v[204:207], v[88:91]
	v_mfma_f32_16x16x32_bf16 v[76:79], v[132:135], v[212:215], v[76:79]
	v_mfma_f32_16x16x32_bf16 v[72:75], v[140:143], v[212:215], v[72:75]
	s_setprio 0
	s_setprio 1
	v_mfma_f32_16x16x32_bf16 v[116:119], v[162:165], v[184:187], v[116:119]
	v_mfma_f32_16x16x32_bf16 v[112:115], v[176:179], v[184:187], v[112:115]
	v_mfma_f32_16x16x32_bf16 v[100:103], v[162:165], v[192:195], v[100:103]
	v_mfma_f32_16x16x32_bf16 v[96:99], v[176:179], v[192:195], v[96:99]
	v_mfma_f32_16x16x32_bf16 v[84:87], v[162:165], v[200:203], v[84:87]
	v_mfma_f32_16x16x32_bf16 v[80:83], v[176:179], v[200:203], v[80:83]
	v_mfma_f32_16x16x32_bf16 v[68:71], v[162:165], v[208:211], v[68:71]
	v_mfma_f32_16x16x32_bf16 v[64:67], v[176:179], v[208:211], v[64:67]
	v_mfma_f32_16x16x32_bf16 v[116:119], v[166:169], v[188:191], v[116:119]
	v_mfma_f32_16x16x32_bf16 v[112:115], v[180:183], v[188:191], v[112:115]
	v_mfma_f32_16x16x32_bf16 v[100:103], v[166:169], v[196:199], v[100:103]
	v_mfma_f32_16x16x32_bf16 v[96:99], v[180:183], v[196:199], v[96:99]
	v_mfma_f32_16x16x32_bf16 v[84:87], v[166:169], v[204:207], v[84:87]
	v_mfma_f32_16x16x32_bf16 v[80:83], v[180:183], v[204:207], v[80:83]
	v_mfma_f32_16x16x32_bf16 v[68:71], v[166:169], v[212:215], v[68:71]
	v_mfma_f32_16x16x32_bf16 v[64:67], v[180:183], v[212:215], v[64:67]
	s_setprio 0
	s_barrier
	s_add_i32 s8, s97, s44
	v_lshl_add_u64 v[216:217], v[216:217], 0, s[78:79]
	s_mov_b32 m0, s8
	ds_read_b128 v[184:187], v175 offset:49152
	ds_read_b128 v[188:191], v175 offset:50176
	ds_read_b128 v[192:195], v175 offset:51200
	ds_read_b128 v[196:199], v175 offset:52224
	ds_read_b128 v[200:203], v175 offset:53248
	ds_read_b128 v[204:207], v175 offset:54272
	ds_read_b128 v[208:211], v175 offset:55296
	ds_read_b128 v[212:215], v175 offset:56320
	global_load_lds_dwordx4 v[216:217], off
	s_add_i32 m0, s8, 0x2000
	s_add_u32 s6, s6, 0x80080
	v_lshl_add_u64 v[216:217], v[218:219], 0, s[78:79]
	s_addc_u32 s7, s7, 0
	s_add_i32 s8, vcc_lo, s44
	global_load_lds_dwordx4 v[216:217], off
	v_lshl_add_u64 v[216:217], s[6:7], 0, v[146:147]
	s_mov_b32 m0, s8
	s_nop 0
	global_load_lds_dwordx4 v[216:217], off
	v_lshl_add_u64 v[216:217], s[6:7], 0, v[144:145]
	s_add_i32 m0, s8, 0x2000
	s_nop 0
	global_load_lds_dwordx4 v[216:217], off
	v_lshl_add_u64 v[216:217], v[220:221], 0, s[78:79]
	s_mov_b32 m0, s71
	s_nop 0
	global_load_lds_dwordx4 v[216:217], off
	v_lshl_add_u64 v[216:217], v[222:223], 0, s[78:79]
	s_mov_b32 m0, s84
	s_nop 0
	global_load_lds_dwordx4 v[216:217], off
	s_waitcnt vmcnt(8)
	s_waitcnt lgkmcnt(0)
	s_barrier
	s_setprio 1
	s_waitcnt lgkmcnt(0)
	v_mfma_f32_16x16x32_bf16 v[60:63], v[128:131], v[184:187], v[60:63]
	v_mfma_f32_16x16x32_bf16 v[56:59], v[136:139], v[184:187], v[56:59]
	v_mfma_f32_16x16x32_bf16 v[44:47], v[128:131], v[192:195], v[44:47]
	v_mfma_f32_16x16x32_bf16 v[40:43], v[136:139], v[192:195], v[40:43]
	v_mfma_f32_16x16x32_bf16 v[28:31], v[128:131], v[200:203], v[28:31]
	v_mfma_f32_16x16x32_bf16 v[24:27], v[136:139], v[200:203], v[24:27]
	v_mfma_f32_16x16x32_bf16 v[12:15], v[128:131], v[208:211], v[12:15]
	v_mfma_f32_16x16x32_bf16 v[8:11], v[136:139], v[208:211], v[8:11]
	v_mfma_f32_16x16x32_bf16 v[60:63], v[132:135], v[188:191], v[60:63]
	v_mfma_f32_16x16x32_bf16 v[56:59], v[140:143], v[188:191], v[56:59]
	v_mfma_f32_16x16x32_bf16 v[44:47], v[132:135], v[196:199], v[44:47]
	v_mfma_f32_16x16x32_bf16 v[40:43], v[140:143], v[196:199], v[40:43]
	v_mfma_f32_16x16x32_bf16 v[28:31], v[132:135], v[204:207], v[28:31]
	v_mfma_f32_16x16x32_bf16 v[24:27], v[140:143], v[204:207], v[24:27]
	v_mfma_f32_16x16x32_bf16 v[12:15], v[132:135], v[212:215], v[12:15]
	v_mfma_f32_16x16x32_bf16 v[8:11], v[140:143], v[212:215], v[8:11]
	s_setprio 0
	s_setprio 1
	v_mfma_f32_16x16x32_bf16 v[52:55], v[162:165], v[184:187], v[52:55]
	v_mfma_f32_16x16x32_bf16 v[48:51], v[176:179], v[184:187], v[48:51]
	v_mfma_f32_16x16x32_bf16 v[36:39], v[162:165], v[192:195], v[36:39]
	v_mfma_f32_16x16x32_bf16 v[32:35], v[176:179], v[192:195], v[32:35]
	v_mfma_f32_16x16x32_bf16 v[20:23], v[162:165], v[200:203], v[20:23]
	v_mfma_f32_16x16x32_bf16 v[16:19], v[176:179], v[200:203], v[16:19]
	v_mfma_f32_16x16x32_bf16 v[4:7], v[162:165], v[208:211], v[4:7]
	v_mfma_f32_16x16x32_bf16 v[0:3], v[176:179], v[208:211], v[0:3]
	v_mfma_f32_16x16x32_bf16 v[52:55], v[166:169], v[188:191], v[52:55]
	v_mfma_f32_16x16x32_bf16 v[48:51], v[180:183], v[188:191], v[48:51]
	v_mfma_f32_16x16x32_bf16 v[36:39], v[166:169], v[196:199], v[36:39]
	v_mfma_f32_16x16x32_bf16 v[32:35], v[180:183], v[196:199], v[32:35]
	v_mfma_f32_16x16x32_bf16 v[20:23], v[166:169], v[204:207], v[20:23]
	v_mfma_f32_16x16x32_bf16 v[16:19], v[180:183], v[204:207], v[16:19]
	v_mfma_f32_16x16x32_bf16 v[4:7], v[166:169], v[212:215], v[4:7]
	v_mfma_f32_16x16x32_bf16 v[0:3], v[180:183], v[212:215], v[0:3]
	s_setprio 0
	s_add_i32 s96, s96, 2
	s_add_u32 s4, s4, 0x100
	s_addc_u32 s5, s5, 0
	s_add_u32 s94, s94, 0x100
	s_addc_u32 s95, s95, 0
	s_cmp_gt_u32 s96, 29
	s_barrier
	s_cbranch_scc0 .LBB0_181
	s_and_b64 vcc, exec, s[88:89]
	s_cbranch_vccz .LBB0_184
	s_barrier

.LBB0_468:
	ds_read_b128 v[128:131], v173
	ds_read_b128 v[132:135], v173 offset:1024
	ds_read_b128 v[136:139], v173 offset:2048
	ds_read_b128 v[140:143], v173 offset:3072
	ds_read_b128 v[162:165], v174
	ds_read_b128 v[166:169], v174 offset:1024
	ds_read_b128 v[176:179], v174 offset:2048
	ds_read_b128 v[180:183], v174 offset:3072
	s_add_u32 s6, s4, 0xfff80080
	s_addc_u32 s7, s5, -1
	s_cmp_eq_u32 s85, 28
	s_cselect_b32 s9, s26, s7
	s_cselect_b32 s8, s27, s6
	s_cselect_b32 s7, s35, s84
	s_cselect_b32 s6, s68, s77
	v_lshl_add_u64 v[216:217], s[4:5], 0, v[158:159]
	s_add_i32 m0, s44, 0xc000
	ds_read_b128 v[184:187], v175
	ds_read_b128 v[188:191], v175 offset:1024
	ds_read_b128 v[192:195], v175 offset:2048
	ds_read_b128 v[196:199], v175 offset:3072
	ds_read_b128 v[200:203], v175 offset:4096
	ds_read_b128 v[204:207], v175 offset:5120
	ds_read_b128 v[208:211], v175 offset:6144
	ds_read_b128 v[212:215], v175 offset:7168
	global_load_lds_dwordx4 v[216:217], off
	v_lshl_add_u64 v[216:217], s[4:5], 0, v[160:161]
	s_add_i32 m0, s44, 0xe000
	s_nop 0
	global_load_lds_dwordx4 v[216:217], off
	s_waitcnt vmcnt(8)
	s_waitcnt lgkmcnt(0)
	s_barrier
	s_setprio 1
	s_waitcnt lgkmcnt(0)
	v_mfma_f32_16x16x32_bf16 v[124:127], v[128:131], v[184:187], v[124:127]
	v_mfma_f32_16x16x32_bf16 v[120:123], v[136:139], v[184:187], v[120:123]
	v_mfma_f32_16x16x32_bf16 v[108:111], v[128:131], v[192:195], v[108:111]
	v_mfma_f32_16x16x32_bf16 v[104:107], v[136:139], v[192:195], v[104:107]
	v_mfma_f32_16x16x32_bf16 v[92:95], v[128:131], v[200:203], v[92:95]
	v_mfma_f32_16x16x32_bf16 v[88:91], v[136:139], v[200:203], v[88:91]
	v_mfma_f32_16x16x32_bf16 v[76:79], v[128:131], v[208:211], v[76:79]
	v_mfma_f32_16x16x32_bf16 v[72:75], v[136:139], v[208:211], v[72:75]
	v_mfma_f32_16x16x32_bf16 v[124:127], v[132:135], v[188:191], v[124:127]
	v_mfma_f32_16x16x32_bf16 v[120:123], v[140:143], v[188:191], v[120:123]
	v_mfma_f32_16x16x32_bf16 v[108:111], v[132:135], v[196:199], v[108:111]
	v_mfma_f32_16x16x32_bf16 v[104:107], v[140:143], v[196:199], v[104:107]
	v_mfma_f32_16x16x32_bf16 v[92:95], v[132:135], v[204:207], v[92:95]
	v_mfma_f32_16x16x32_bf16 v[88:91], v[140:143], v[204:207], v[88:91]
	v_mfma_f32_16x16x32_bf16 v[76:79], v[132:135], v[212:215], v[76:79]
	v_mfma_f32_16x16x32_bf16 v[72:75], v[140:143], v[212:215], v[72:75]
	s_setprio 0
	s_setprio 1
	v_mfma_f32_16x16x32_bf16 v[116:119], v[162:165], v[184:187], v[116:119]
	v_mfma_f32_16x16x32_bf16 v[112:115], v[176:179], v[184:187], v[112:115]
	v_mfma_f32_16x16x32_bf16 v[100:103], v[162:165], v[192:195], v[100:103]
	v_mfma_f32_16x16x32_bf16 v[96:99], v[176:179], v[192:195], v[96:99]
	v_mfma_f32_16x16x32_bf16 v[84:87], v[162:165], v[200:203], v[84:87]
	v_mfma_f32_16x16x32_bf16 v[80:83], v[176:179], v[200:203], v[80:83]
	v_mfma_f32_16x16x32_bf16 v[68:71], v[162:165], v[208:211], v[68:71]
	v_mfma_f32_16x16x32_bf16 v[64:67], v[176:179], v[208:211], v[64:67]
	v_mfma_f32_16x16x32_bf16 v[116:119], v[166:169], v[188:191], v[116:119]
	v_mfma_f32_16x16x32_bf16 v[112:115], v[180:183], v[188:191], v[112:115]
	v_mfma_f32_16x16x32_bf16 v[100:103], v[166:169], v[196:199], v[100:103]
	v_mfma_f32_16x16x32_bf16 v[96:99], v[180:183], v[196:199], v[96:99]
	v_mfma_f32_16x16x32_bf16 v[84:87], v[166:169], v[204:207], v[84:87]
	v_mfma_f32_16x16x32_bf16 v[80:83], v[180:183], v[204:207], v[80:83]
	v_mfma_f32_16x16x32_bf16 v[68:71], v[166:169], v[212:215], v[68:71]
	v_mfma_f32_16x16x32_bf16 v[64:67], v[180:183], v[212:215], v[64:67]
	s_setprio 0
	s_barrier
	s_add_i32 s89, s51, s43
	v_lshl_add_u64 v[216:217], s[6:7], 0, v[144:145]
	s_mov_b32 m0, s89
	ds_read_b128 v[184:187], v175 offset:16384
	ds_read_b128 v[188:191], v175 offset:17408
	ds_read_b128 v[192:195], v175 offset:18432
	ds_read_b128 v[196:199], v175 offset:19456
	ds_read_b128 v[200:203], v175 offset:20480
	ds_read_b128 v[204:207], v175 offset:21504
	ds_read_b128 v[208:211], v175 offset:22528
	ds_read_b128 v[212:215], v175 offset:23552
	global_load_lds_dwordx4 v[216:217], off
	s_add_i32 m0, s89, 0x2000
	s_add_u32 s90, s6, 0x80000
	v_lshl_add_u64 v[218:219], s[6:7], 0, v[146:147]
	s_addc_u32 s91, s7, 0
	s_add_i32 s89, s65, s43
	global_load_lds_dwordx4 v[218:219], off
	v_lshl_add_u64 v[220:221], s[90:91], 0, v[144:145]
	s_mov_b32 m0, s89
	v_lshl_add_u64 v[222:223], s[8:9], 0, v[146:147]
	global_load_lds_dwordx4 v[220:221], off
	v_lshl_add_u64 v[220:221], s[90:91], 0, v[146:147]
	s_add_i32 m0, s89, 0x2000
	s_nop 0
	global_load_lds_dwordx4 v[220:221], off
	v_lshl_add_u64 v[220:221], s[8:9], 0, v[144:145]
	s_mov_b32 m0, s44
	s_nop 0
	global_load_lds_dwordx4 v[220:221], off
	s_mov_b32 m0, s45
	s_nop 0
	global_load_lds_dwordx4 v[222:223], off
	s_waitcnt vmcnt(8)
	s_waitcnt lgkmcnt(0)
	s_barrier
	s_setprio 1
	s_waitcnt lgkmcnt(0)
	v_mfma_f32_16x16x32_bf16 v[60:63], v[128:131], v[184:187], v[60:63]
	v_mfma_f32_16x16x32_bf16 v[56:59], v[136:139], v[184:187], v[56:59]
	v_mfma_f32_16x16x32_bf16 v[44:47], v[128:131], v[192:195], v[44:47]
	v_mfma_f32_16x16x32_bf16 v[40:43], v[136:139], v[192:195], v[40:43]
	v_mfma_f32_16x16x32_bf16 v[28:31], v[128:131], v[200:203], v[28:31]
	v_mfma_f32_16x16x32_bf16 v[24:27], v[136:139], v[200:203], v[24:27]
	v_mfma_f32_16x16x32_bf16 v[12:15], v[128:131], v[208:211], v[12:15]
	v_mfma_f32_16x16x32_bf16 v[8:11], v[136:139], v[208:211], v[8:11]
	v_mfma_f32_16x16x32_bf16 v[60:63], v[132:135], v[188:191], v[60:63]
	v_mfma_f32_16x16x32_bf16 v[56:59], v[140:143], v[188:191], v[56:59]
	v_mfma_f32_16x16x32_bf16 v[44:47], v[132:135], v[196:199], v[44:47]
	v_mfma_f32_16x16x32_bf16 v[40:43], v[140:143], v[196:199], v[40:43]
	v_mfma_f32_16x16x32_bf16 v[28:31], v[132:135], v[204:207], v[28:31]
	v_mfma_f32_16x16x32_bf16 v[24:27], v[140:143], v[204:207], v[24:27]
	v_mfma_f32_16x16x32_bf16 v[12:15], v[132:135], v[212:215], v[12:15]
	v_mfma_f32_16x16x32_bf16 v[8:11], v[140:143], v[212:215], v[8:11]
	s_setprio 0
	s_setprio 1
	v_mfma_f32_16x16x32_bf16 v[52:55], v[162:165], v[184:187], v[52:55]
	v_mfma_f32_16x16x32_bf16 v[48:51], v[176:179], v[184:187], v[48:51]
	v_mfma_f32_16x16x32_bf16 v[36:39], v[162:165], v[192:195], v[36:39]
	v_mfma_f32_16x16x32_bf16 v[32:35], v[176:179], v[192:195], v[32:35]
	v_mfma_f32_16x16x32_bf16 v[20:23], v[162:165], v[200:203], v[20:23]
	v_mfma_f32_16x16x32_bf16 v[16:19], v[176:179], v[200:203], v[16:19]
	v_mfma_f32_16x16x32_bf16 v[4:7], v[162:165], v[208:211], v[4:7]
	v_mfma_f32_16x16x32_bf16 v[0:3], v[176:179], v[208:211], v[0:3]
	v_mfma_f32_16x16x32_bf16 v[52:55], v[166:169], v[188:191], v[52:55]
	v_mfma_f32_16x16x32_bf16 v[48:51], v[180:183], v[188:191], v[48:51]
	v_mfma_f32_16x16x32_bf16 v[36:39], v[166:169], v[196:199], v[36:39]
	v_mfma_f32_16x16x32_bf16 v[32:35], v[180:183], v[196:199], v[32:35]
	v_mfma_f32_16x16x32_bf16 v[20:23], v[166:169], v[204:207], v[20:23]
	v_mfma_f32_16x16x32_bf16 v[16:19], v[180:183], v[204:207], v[16:19]
	v_mfma_f32_16x16x32_bf16 v[4:7], v[166:169], v[212:215], v[4:7]
	v_mfma_f32_16x16x32_bf16 v[0:3], v[180:183], v[212:215], v[0:3]
	s_setprio 0
	s_barrier
	s_add_i32 s89, 0, 0x18000
	s_add_i32 s90, 0, 0x1c000
	v_add_u32_e32 v140, s89, v153
	v_add_u32_e32 v180, s90, v153
	ds_read_b128 v[128:131], v140
	ds_read_b128 v[132:135], v140 offset:1024
	ds_read_b128 v[136:139], v140 offset:2048
	ds_read_b128 v[140:143], v140 offset:3072
	ds_read_b128 v[162:165], v180
	ds_read_b128 v[166:169], v180 offset:1024
	ds_read_b128 v[176:179], v180 offset:2048
	ds_read_b128 v[180:183], v180 offset:3072
	s_add_u32 s8, s8, 0x80000
	s_addc_u32 s9, s9, 0
	s_mov_b32 m0, s46
	v_lshl_add_u64 v[224:225], s[8:9], 0, v[144:145]
	ds_read_b128 v[184:187], v175 offset:32768
	ds_read_b128 v[188:191], v175 offset:33792
	ds_read_b128 v[192:195], v175 offset:34816
	ds_read_b128 v[196:199], v175 offset:35840
	ds_read_b128 v[200:203], v175 offset:36864
	ds_read_b128 v[204:207], v175 offset:37888
	ds_read_b128 v[208:211], v175 offset:38912
	ds_read_b128 v[212:215], v175 offset:39936
	global_load_lds_dwordx4 v[224:225], off
	v_lshl_add_u64 v[224:225], s[8:9], 0, v[146:147]
	s_mov_b32 m0, s47
	s_nop 0
	global_load_lds_dwordx4 v[224:225], off
	s_waitcnt vmcnt(8)
	s_waitcnt lgkmcnt(0)
	s_barrier
	s_setprio 1
	s_waitcnt lgkmcnt(0)
	v_mfma_f32_16x16x32_bf16 v[124:127], v[128:131], v[184:187], v[124:127]
	v_mfma_f32_16x16x32_bf16 v[120:123], v[136:139], v[184:187], v[120:123]
	v_mfma_f32_16x16x32_bf16 v[108:111], v[128:131], v[192:195], v[108:111]
	v_mfma_f32_16x16x32_bf16 v[104:107], v[136:139], v[192:195], v[104:107]
	v_mfma_f32_16x16x32_bf16 v[92:95], v[128:131], v[200:203], v[92:95]
	v_mfma_f32_16x16x32_bf16 v[88:91], v[136:139], v[200:203], v[88:91]
	v_mfma_f32_16x16x32_bf16 v[76:79], v[128:131], v[208:211], v[76:79]
	v_mfma_f32_16x16x32_bf16 v[72:75], v[136:139], v[208:211], v[72:75]
	v_mfma_f32_16x16x32_bf16 v[124:127], v[132:135], v[188:191], v[124:127]
	v_mfma_f32_16x16x32_bf16 v[120:123], v[140:143], v[188:191], v[120:123]
	v_mfma_f32_16x16x32_bf16 v[108:111], v[132:135], v[196:199], v[108:111]
	v_mfma_f32_16x16x32_bf16 v[104:107], v[140:143], v[196:199], v[104:107]
	v_mfma_f32_16x16x32_bf16 v[92:95], v[132:135], v[204:207], v[92:95]
	v_mfma_f32_16x16x32_bf16 v[88:91], v[140:143], v[204:207], v[88:91]
	v_mfma_f32_16x16x32_bf16 v[76:79], v[132:135], v[212:215], v[76:79]
	v_mfma_f32_16x16x32_bf16 v[72:75], v[140:143], v[212:215], v[72:75]
	s_setprio 0
	s_setprio 1
	v_mfma_f32_16x16x32_bf16 v[116:119], v[162:165], v[184:187], v[116:119]
	v_mfma_f32_16x16x32_bf16 v[112:115], v[176:179], v[184:187], v[112:115]
	v_mfma_f32_16x16x32_bf16 v[100:103], v[162:165], v[192:195], v[100:103]
	v_mfma_f32_16x16x32_bf16 v[96:99], v[176:179], v[192:195], v[96:99]
	v_mfma_f32_16x16x32_bf16 v[84:87], v[162:165], v[200:203], v[84:87]
	v_mfma_f32_16x16x32_bf16 v[80:83], v[176:179], v[200:203], v[80:83]
	v_mfma_f32_16x16x32_bf16 v[68:71], v[162:165], v[208:211], v[68:71]
	v_mfma_f32_16x16x32_bf16 v[64:67], v[176:179], v[208:211], v[64:67]
	v_mfma_f32_16x16x32_bf16 v[116:119], v[166:169], v[188:191], v[116:119]
	v_mfma_f32_16x16x32_bf16 v[112:115], v[180:183], v[188:191], v[112:115]
	v_mfma_f32_16x16x32_bf16 v[100:103], v[166:169], v[196:199], v[100:103]
	v_mfma_f32_16x16x32_bf16 v[96:99], v[180:183], v[196:199], v[96:99]
	v_mfma_f32_16x16x32_bf16 v[84:87], v[166:169], v[204:207], v[84:87]
	v_mfma_f32_16x16x32_bf16 v[80:83], v[180:183], v[204:207], v[80:83]
	v_mfma_f32_16x16x32_bf16 v[68:71], v[166:169], v[212:215], v[68:71]
	v_mfma_f32_16x16x32_bf16 v[64:67], v[180:183], v[212:215], v[64:67]
	s_setprio 0
	s_barrier
	s_add_i32 s8, s89, s43
	v_lshl_add_u64 v[216:217], v[216:217], 0, s[72:73]
	s_mov_b32 m0, s8
	ds_read_b128 v[184:187], v175 offset:49152
	ds_read_b128 v[188:191], v175 offset:50176
	ds_read_b128 v[192:195], v175 offset:51200
	ds_read_b128 v[196:199], v175 offset:52224
	ds_read_b128 v[200:203], v175 offset:53248
	ds_read_b128 v[204:207], v175 offset:54272
	ds_read_b128 v[208:211], v175 offset:55296
	ds_read_b128 v[212:215], v175 offset:56320
	global_load_lds_dwordx4 v[216:217], off
	s_add_i32 m0, s8, 0x2000
	s_add_u32 s6, s6, 0x80080
	v_lshl_add_u64 v[216:217], v[218:219], 0, s[72:73]
	s_addc_u32 s7, s7, 0
	s_add_i32 s8, s90, s43
	global_load_lds_dwordx4 v[216:217], off
	v_lshl_add_u64 v[216:217], s[6:7], 0, v[144:145]
	s_mov_b32 m0, s8
	s_nop 0
	global_load_lds_dwordx4 v[216:217], off
	v_lshl_add_u64 v[216:217], s[6:7], 0, v[146:147]
	s_add_i32 m0, s8, 0x2000
	s_nop 0
	global_load_lds_dwordx4 v[216:217], off
	v_lshl_add_u64 v[216:217], v[220:221], 0, s[72:73]
	s_mov_b32 m0, s49
	s_nop 0
	global_load_lds_dwordx4 v[216:217], off
	v_lshl_add_u64 v[216:217], v[222:223], 0, s[72:73]
	s_mov_b32 m0, s50
	s_nop 0
	global_load_lds_dwordx4 v[216:217], off
	s_waitcnt vmcnt(8)
	s_waitcnt lgkmcnt(0)
	s_barrier
	s_setprio 1
	s_waitcnt lgkmcnt(0)
	v_mfma_f32_16x16x32_bf16 v[60:63], v[128:131], v[184:187], v[60:63]
	v_mfma_f32_16x16x32_bf16 v[56:59], v[136:139], v[184:187], v[56:59]
	v_mfma_f32_16x16x32_bf16 v[44:47], v[128:131], v[192:195], v[44:47]
	v_mfma_f32_16x16x32_bf16 v[40:43], v[136:139], v[192:195], v[40:43]
	v_mfma_f32_16x16x32_bf16 v[28:31], v[128:131], v[200:203], v[28:31]
	v_mfma_f32_16x16x32_bf16 v[24:27], v[136:139], v[200:203], v[24:27]
	v_mfma_f32_16x16x32_bf16 v[12:15], v[128:131], v[208:211], v[12:15]
	v_mfma_f32_16x16x32_bf16 v[8:11], v[136:139], v[208:211], v[8:11]
	v_mfma_f32_16x16x32_bf16 v[60:63], v[132:135], v[188:191], v[60:63]
	v_mfma_f32_16x16x32_bf16 v[56:59], v[140:143], v[188:191], v[56:59]
	v_mfma_f32_16x16x32_bf16 v[44:47], v[132:135], v[196:199], v[44:47]
	v_mfma_f32_16x16x32_bf16 v[40:43], v[140:143], v[196:199], v[40:43]
	v_mfma_f32_16x16x32_bf16 v[28:31], v[132:135], v[204:207], v[28:31]
	v_mfma_f32_16x16x32_bf16 v[24:27], v[140:143], v[204:207], v[24:27]
	v_mfma_f32_16x16x32_bf16 v[12:15], v[132:135], v[212:215], v[12:15]
	v_mfma_f32_16x16x32_bf16 v[8:11], v[140:143], v[212:215], v[8:11]
	s_setprio 0
	s_setprio 1
	v_mfma_f32_16x16x32_bf16 v[52:55], v[162:165], v[184:187], v[52:55]
	v_mfma_f32_16x16x32_bf16 v[48:51], v[176:179], v[184:187], v[48:51]
	v_mfma_f32_16x16x32_bf16 v[36:39], v[162:165], v[192:195], v[36:39]
	v_mfma_f32_16x16x32_bf16 v[32:35], v[176:179], v[192:195], v[32:35]
	v_mfma_f32_16x16x32_bf16 v[20:23], v[162:165], v[200:203], v[20:23]
	v_mfma_f32_16x16x32_bf16 v[16:19], v[176:179], v[200:203], v[16:19]
	v_mfma_f32_16x16x32_bf16 v[4:7], v[162:165], v[208:211], v[4:7]
	v_mfma_f32_16x16x32_bf16 v[0:3], v[176:179], v[208:211], v[0:3]
	v_mfma_f32_16x16x32_bf16 v[52:55], v[166:169], v[188:191], v[52:55]
	v_mfma_f32_16x16x32_bf16 v[48:51], v[180:183], v[188:191], v[48:51]
	v_mfma_f32_16x16x32_bf16 v[36:39], v[166:169], v[196:199], v[36:39]
	v_mfma_f32_16x16x32_bf16 v[32:35], v[180:183], v[196:199], v[32:35]
	v_mfma_f32_16x16x32_bf16 v[20:23], v[166:169], v[204:207], v[20:23]
	v_mfma_f32_16x16x32_bf16 v[16:19], v[180:183], v[204:207], v[16:19]
	v_mfma_f32_16x16x32_bf16 v[4:7], v[166:169], v[212:215], v[4:7]
	v_mfma_f32_16x16x32_bf16 v[0:3], v[180:183], v[212:215], v[0:3]
	s_setprio 0
	s_add_i32 s85, s85, 2
	s_add_u32 s4, s4, 0x100
	s_addc_u32 s5, s5, 0
	s_add_u32 s77, s77, 0x100
	s_addc_u32 s84, s84, 0
	s_cmp_gt_u32 s85, 29
	s_barrier
	s_cbranch_scc0 .LBB0_468
	s_and_b64 vcc, exec, s[74:75]
	s_cbranch_vccz .LBB0_471
	s_barrier

.LBB0_797:
	ds_read_b128 v[152:155], v146
	ds_read_b128 v[156:159], v146 offset:1024
	ds_read_b128 v[160:163], v146 offset:2048
	ds_read_b128 v[164:167], v146 offset:3072
	ds_read_b128 v[168:171], v147
	ds_read_b128 v[172:175], v147 offset:1024
	ds_read_b128 v[176:179], v147 offset:2048
	ds_read_b128 v[180:183], v147 offset:3072
	s_add_u32 s22, s20, 0xf8980080
	s_addc_u32 s23, s21, -1
	s_cmp_lg_u32 s46, 28
	s_cselect_b32 s22, s22, 0
	s_cselect_b32 s23, s23, 0
	s_add_u32 s24, s12, s22
	s_addc_u32 s25, s13, s23
	s_add_u32 s22, s6, s22
	s_addc_u32 s23, s7, s23
	s_mov_b32 m0, s47
	v_lshl_add_u64 v[216:217], v[138:139], 0, s[20:21]
	ds_read_b128 v[184:187], v148
	ds_read_b128 v[188:191], v148 offset:1024
	ds_read_b128 v[192:195], v148 offset:2048
	ds_read_b128 v[196:199], v148 offset:3072
	ds_read_b128 v[200:203], v148 offset:4096
	ds_read_b128 v[204:207], v148 offset:5120
	ds_read_b128 v[208:211], v148 offset:6144
	ds_read_b128 v[212:215], v148 offset:7168
	global_load_lds_dwordx4 v[216:217], off
	v_lshl_add_u64 v[216:217], v[140:141], 0, s[20:21]
	s_mov_b32 m0, s48
	s_nop 0
	global_load_lds_dwordx4 v[216:217], off
	s_waitcnt vmcnt(8)
	s_waitcnt lgkmcnt(0)
	s_barrier
	s_setprio 1
	s_waitcnt lgkmcnt(0)
	v_mfma_f32_16x16x32_bf16 v[124:127], v[152:155], v[184:187], v[124:127]
	v_mfma_f32_16x16x32_bf16 v[120:123], v[160:163], v[184:187], v[120:123]
	v_mfma_f32_16x16x32_bf16 v[108:111], v[152:155], v[192:195], v[108:111]
	v_mfma_f32_16x16x32_bf16 v[104:107], v[160:163], v[192:195], v[104:107]
	v_mfma_f32_16x16x32_bf16 v[92:95], v[152:155], v[200:203], v[92:95]
	v_mfma_f32_16x16x32_bf16 v[88:91], v[160:163], v[200:203], v[88:91]
	v_mfma_f32_16x16x32_bf16 v[76:79], v[152:155], v[208:211], v[76:79]
	v_mfma_f32_16x16x32_bf16 v[72:75], v[160:163], v[208:211], v[72:75]
	v_mfma_f32_16x16x32_bf16 v[124:127], v[156:159], v[188:191], v[124:127]
	v_mfma_f32_16x16x32_bf16 v[120:123], v[164:167], v[188:191], v[120:123]
	v_mfma_f32_16x16x32_bf16 v[108:111], v[156:159], v[196:199], v[108:111]
	v_mfma_f32_16x16x32_bf16 v[104:107], v[164:167], v[196:199], v[104:107]
	v_mfma_f32_16x16x32_bf16 v[92:95], v[156:159], v[204:207], v[92:95]
	v_mfma_f32_16x16x32_bf16 v[88:91], v[164:167], v[204:207], v[88:91]
	v_mfma_f32_16x16x32_bf16 v[76:79], v[156:159], v[212:215], v[76:79]
	v_mfma_f32_16x16x32_bf16 v[72:75], v[164:167], v[212:215], v[72:75]
	s_setprio 0
	s_setprio 1
	v_mfma_f32_16x16x32_bf16 v[116:119], v[168:171], v[184:187], v[116:119]
	v_mfma_f32_16x16x32_bf16 v[112:115], v[176:179], v[184:187], v[112:115]
	v_mfma_f32_16x16x32_bf16 v[100:103], v[168:171], v[192:195], v[100:103]
	v_mfma_f32_16x16x32_bf16 v[96:99], v[176:179], v[192:195], v[96:99]
	v_mfma_f32_16x16x32_bf16 v[84:87], v[168:171], v[200:203], v[84:87]
	v_mfma_f32_16x16x32_bf16 v[80:83], v[176:179], v[200:203], v[80:83]
	v_mfma_f32_16x16x32_bf16 v[68:71], v[168:171], v[208:211], v[68:71]
	v_mfma_f32_16x16x32_bf16 v[64:67], v[176:179], v[208:211], v[64:67]
	v_mfma_f32_16x16x32_bf16 v[116:119], v[172:175], v[188:191], v[116:119]
	v_mfma_f32_16x16x32_bf16 v[112:115], v[180:183], v[188:191], v[112:115]
	v_mfma_f32_16x16x32_bf16 v[100:103], v[172:175], v[196:199], v[100:103]
	v_mfma_f32_16x16x32_bf16 v[96:99], v[180:183], v[196:199], v[96:99]
	v_mfma_f32_16x16x32_bf16 v[84:87], v[172:175], v[204:207], v[84:87]
	v_mfma_f32_16x16x32_bf16 v[80:83], v[180:183], v[204:207], v[80:83]
	v_mfma_f32_16x16x32_bf16 v[68:71], v[172:175], v[212:215], v[68:71]
	v_mfma_f32_16x16x32_bf16 v[64:67], v[180:183], v[212:215], v[64:67]
	s_setprio 0
	s_barrier
	s_mov_b32 m0, s49
	v_lshl_add_u64 v[216:217], s[22:23], 0, v[128:129]
	s_add_u32 s86, s22, 0x80000
	ds_read_b128 v[184:187], v148 offset:16384
	ds_read_b128 v[188:191], v148 offset:17408
	ds_read_b128 v[192:195], v148 offset:18432
	ds_read_b128 v[196:199], v148 offset:19456
	ds_read_b128 v[200:203], v148 offset:20480
	ds_read_b128 v[204:207], v148 offset:21504
	ds_read_b128 v[208:211], v148 offset:22528
	ds_read_b128 v[212:215], v148 offset:23552
	global_load_lds_dwordx4 v[216:217], off
	v_lshl_add_u64 v[218:219], s[22:23], 0, v[130:131]
	s_mov_b32 m0, s50
	s_addc_u32 s87, s23, 0
	global_load_lds_dwordx4 v[218:219], off
	v_lshl_add_u64 v[220:221], s[86:87], 0, v[128:129]
	s_mov_b32 m0, s51
	v_lshl_add_u64 v[222:223], s[24:25], 0, v[130:131]
	global_load_lds_dwordx4 v[220:221], off
	v_lshl_add_u64 v[220:221], s[86:87], 0, v[130:131]
	s_mov_b32 m0, s56
	s_nop 0
	global_load_lds_dwordx4 v[220:221], off
	v_lshl_add_u64 v[220:221], s[24:25], 0, v[128:129]
	s_mov_b32 m0, s5
	s_nop 0
	global_load_lds_dwordx4 v[220:221], off
	s_mov_b32 m0, s39
	s_nop 0
	global_load_lds_dwordx4 v[222:223], off
	s_waitcnt vmcnt(8)
	s_waitcnt lgkmcnt(0)
	s_barrier
	s_setprio 1
	s_waitcnt lgkmcnt(0)
	v_mfma_f32_16x16x32_bf16 v[60:63], v[152:155], v[184:187], v[60:63]
	v_mfma_f32_16x16x32_bf16 v[56:59], v[160:163], v[184:187], v[56:59]
	v_mfma_f32_16x16x32_bf16 v[44:47], v[152:155], v[192:195], v[44:47]
	v_mfma_f32_16x16x32_bf16 v[40:43], v[160:163], v[192:195], v[40:43]
	v_mfma_f32_16x16x32_bf16 v[28:31], v[152:155], v[200:203], v[28:31]
	v_mfma_f32_16x16x32_bf16 v[24:27], v[160:163], v[200:203], v[24:27]
	v_mfma_f32_16x16x32_bf16 v[12:15], v[152:155], v[208:211], v[12:15]
	v_mfma_f32_16x16x32_bf16 v[8:11], v[160:163], v[208:211], v[8:11]
	v_mfma_f32_16x16x32_bf16 v[60:63], v[156:159], v[188:191], v[60:63]
	v_mfma_f32_16x16x32_bf16 v[56:59], v[164:167], v[188:191], v[56:59]
	v_mfma_f32_16x16x32_bf16 v[44:47], v[156:159], v[196:199], v[44:47]
	v_mfma_f32_16x16x32_bf16 v[40:43], v[164:167], v[196:199], v[40:43]
	v_mfma_f32_16x16x32_bf16 v[28:31], v[156:159], v[204:207], v[28:31]
	v_mfma_f32_16x16x32_bf16 v[24:27], v[164:167], v[204:207], v[24:27]
	v_mfma_f32_16x16x32_bf16 v[12:15], v[156:159], v[212:215], v[12:15]
	v_mfma_f32_16x16x32_bf16 v[8:11], v[164:167], v[212:215], v[8:11]
	s_setprio 0
	s_setprio 1
	v_mfma_f32_16x16x32_bf16 v[52:55], v[168:171], v[184:187], v[52:55]
	v_mfma_f32_16x16x32_bf16 v[48:51], v[176:179], v[184:187], v[48:51]
	v_mfma_f32_16x16x32_bf16 v[36:39], v[168:171], v[192:195], v[36:39]
	v_mfma_f32_16x16x32_bf16 v[32:35], v[176:179], v[192:195], v[32:35]
	v_mfma_f32_16x16x32_bf16 v[20:23], v[168:171], v[200:203], v[20:23]
	v_mfma_f32_16x16x32_bf16 v[16:19], v[176:179], v[200:203], v[16:19]
	v_mfma_f32_16x16x32_bf16 v[4:7], v[168:171], v[208:211], v[4:7]
	v_mfma_f32_16x16x32_bf16 v[0:3], v[176:179], v[208:211], v[0:3]
	v_mfma_f32_16x16x32_bf16 v[52:55], v[172:175], v[188:191], v[52:55]
	v_mfma_f32_16x16x32_bf16 v[48:51], v[180:183], v[188:191], v[48:51]
	v_mfma_f32_16x16x32_bf16 v[36:39], v[172:175], v[196:199], v[36:39]
	v_mfma_f32_16x16x32_bf16 v[32:35], v[180:183], v[196:199], v[32:35]
	v_mfma_f32_16x16x32_bf16 v[20:23], v[172:175], v[204:207], v[20:23]
	v_mfma_f32_16x16x32_bf16 v[16:19], v[180:183], v[204:207], v[16:19]
	v_mfma_f32_16x16x32_bf16 v[4:7], v[172:175], v[212:215], v[4:7]
	v_mfma_f32_16x16x32_bf16 v[0:3], v[180:183], v[212:215], v[0:3]
	s_setprio 0
	s_barrier
	ds_read_b128 v[152:155], v149
	ds_read_b128 v[156:159], v149 offset:1024
	ds_read_b128 v[160:163], v149 offset:2048
	ds_read_b128 v[164:167], v149 offset:3072
	ds_read_b128 v[168:171], v150
	ds_read_b128 v[172:175], v150 offset:1024
	ds_read_b128 v[176:179], v150 offset:2048
	ds_read_b128 v[180:183], v150 offset:3072
	s_add_u32 s24, s24, 0x80000
	s_addc_u32 s25, s25, 0
	s_mov_b32 m0, s40
	v_lshl_add_u64 v[224:225], s[24:25], 0, v[128:129]
	ds_read_b128 v[184:187], v148 offset:32768
	ds_read_b128 v[188:191], v148 offset:33792
	ds_read_b128 v[192:195], v148 offset:34816
	ds_read_b128 v[196:199], v148 offset:35840
	ds_read_b128 v[200:203], v148 offset:36864
	ds_read_b128 v[204:207], v148 offset:37888
	ds_read_b128 v[208:211], v148 offset:38912
	ds_read_b128 v[212:215], v148 offset:39936
	global_load_lds_dwordx4 v[224:225], off
	v_lshl_add_u64 v[224:225], s[24:25], 0, v[130:131]
	s_mov_b32 m0, s42
	s_nop 0
	global_load_lds_dwordx4 v[224:225], off
	s_waitcnt vmcnt(8)
	s_waitcnt lgkmcnt(0)
	s_barrier
	s_setprio 1
	s_waitcnt lgkmcnt(0)
	v_mfma_f32_16x16x32_bf16 v[124:127], v[152:155], v[184:187], v[124:127]
	v_mfma_f32_16x16x32_bf16 v[120:123], v[160:163], v[184:187], v[120:123]
	v_mfma_f32_16x16x32_bf16 v[108:111], v[152:155], v[192:195], v[108:111]
	v_mfma_f32_16x16x32_bf16 v[104:107], v[160:163], v[192:195], v[104:107]
	v_mfma_f32_16x16x32_bf16 v[92:95], v[152:155], v[200:203], v[92:95]
	v_mfma_f32_16x16x32_bf16 v[88:91], v[160:163], v[200:203], v[88:91]
	v_mfma_f32_16x16x32_bf16 v[76:79], v[152:155], v[208:211], v[76:79]
	v_mfma_f32_16x16x32_bf16 v[72:75], v[160:163], v[208:211], v[72:75]
	v_mfma_f32_16x16x32_bf16 v[124:127], v[156:159], v[188:191], v[124:127]
	v_mfma_f32_16x16x32_bf16 v[120:123], v[164:167], v[188:191], v[120:123]
	v_mfma_f32_16x16x32_bf16 v[108:111], v[156:159], v[196:199], v[108:111]
	v_mfma_f32_16x16x32_bf16 v[104:107], v[164:167], v[196:199], v[104:107]
	v_mfma_f32_16x16x32_bf16 v[92:95], v[156:159], v[204:207], v[92:95]
	v_mfma_f32_16x16x32_bf16 v[88:91], v[164:167], v[204:207], v[88:91]
	v_mfma_f32_16x16x32_bf16 v[76:79], v[156:159], v[212:215], v[76:79]
	v_mfma_f32_16x16x32_bf16 v[72:75], v[164:167], v[212:215], v[72:75]
	s_setprio 0
	s_setprio 1
	v_mfma_f32_16x16x32_bf16 v[116:119], v[168:171], v[184:187], v[116:119]
	v_mfma_f32_16x16x32_bf16 v[112:115], v[176:179], v[184:187], v[112:115]
	v_mfma_f32_16x16x32_bf16 v[100:103], v[168:171], v[192:195], v[100:103]
	v_mfma_f32_16x16x32_bf16 v[96:99], v[176:179], v[192:195], v[96:99]
	v_mfma_f32_16x16x32_bf16 v[84:87], v[168:171], v[200:203], v[84:87]
	v_mfma_f32_16x16x32_bf16 v[80:83], v[176:179], v[200:203], v[80:83]
	v_mfma_f32_16x16x32_bf16 v[68:71], v[168:171], v[208:211], v[68:71]
	v_mfma_f32_16x16x32_bf16 v[64:67], v[176:179], v[208:211], v[64:67]
	v_mfma_f32_16x16x32_bf16 v[116:119], v[172:175], v[188:191], v[116:119]
	v_mfma_f32_16x16x32_bf16 v[112:115], v[180:183], v[188:191], v[112:115]
	v_mfma_f32_16x16x32_bf16 v[100:103], v[172:175], v[196:199], v[100:103]
	v_mfma_f32_16x16x32_bf16 v[96:99], v[180:183], v[196:199], v[96:99]
	v_mfma_f32_16x16x32_bf16 v[84:87], v[172:175], v[204:207], v[84:87]
	v_mfma_f32_16x16x32_bf16 v[80:83], v[180:183], v[204:207], v[80:83]
	v_mfma_f32_16x16x32_bf16 v[68:71], v[172:175], v[212:215], v[68:71]
	v_mfma_f32_16x16x32_bf16 v[64:67], v[180:183], v[212:215], v[64:67]
	s_setprio 0
	s_barrier
	s_mov_b32 m0, s57
	v_lshl_add_u64 v[216:217], v[216:217], 0, s[2:3]
	s_add_u32 s22, s22, 0x80080
	ds_read_b128 v[184:187], v148 offset:49152
	ds_read_b128 v[188:191], v148 offset:50176
	ds_read_b128 v[192:195], v148 offset:51200
	ds_read_b128 v[196:199], v148 offset:52224
	ds_read_b128 v[200:203], v148 offset:53248
	ds_read_b128 v[204:207], v148 offset:54272
	ds_read_b128 v[208:211], v148 offset:55296
	ds_read_b128 v[212:215], v148 offset:56320
	global_load_lds_dwordx4 v[216:217], off
	v_lshl_add_u64 v[216:217], v[218:219], 0, s[2:3]
	s_mov_b32 m0, s58
	s_addc_u32 s23, s23, 0
	global_load_lds_dwordx4 v[216:217], off
	v_lshl_add_u64 v[216:217], s[22:23], 0, v[128:129]
	s_mov_b32 m0, s59
	s_nop 0
	global_load_lds_dwordx4 v[216:217], off
	v_lshl_add_u64 v[216:217], s[22:23], 0, v[130:131]
	s_mov_b32 m0, s84
	s_nop 0
	global_load_lds_dwordx4 v[216:217], off
	v_lshl_add_u64 v[216:217], v[220:221], 0, s[2:3]
	s_mov_b32 m0, s44
	s_nop 0
	global_load_lds_dwordx4 v[216:217], off
	v_lshl_add_u64 v[216:217], v[222:223], 0, s[2:3]
	s_mov_b32 m0, s45
	s_nop 0
	global_load_lds_dwordx4 v[216:217], off
	s_waitcnt vmcnt(8)
	s_waitcnt lgkmcnt(0)
	s_barrier
	s_setprio 1
	s_waitcnt lgkmcnt(0)
	v_mfma_f32_16x16x32_bf16 v[60:63], v[152:155], v[184:187], v[60:63]
	v_mfma_f32_16x16x32_bf16 v[56:59], v[160:163], v[184:187], v[56:59]
	v_mfma_f32_16x16x32_bf16 v[44:47], v[152:155], v[192:195], v[44:47]
	v_mfma_f32_16x16x32_bf16 v[40:43], v[160:163], v[192:195], v[40:43]
	v_mfma_f32_16x16x32_bf16 v[28:31], v[152:155], v[200:203], v[28:31]
	v_mfma_f32_16x16x32_bf16 v[24:27], v[160:163], v[200:203], v[24:27]
	v_mfma_f32_16x16x32_bf16 v[12:15], v[152:155], v[208:211], v[12:15]
	v_mfma_f32_16x16x32_bf16 v[8:11], v[160:163], v[208:211], v[8:11]
	v_mfma_f32_16x16x32_bf16 v[60:63], v[156:159], v[188:191], v[60:63]
	v_mfma_f32_16x16x32_bf16 v[56:59], v[164:167], v[188:191], v[56:59]
	v_mfma_f32_16x16x32_bf16 v[44:47], v[156:159], v[196:199], v[44:47]
	v_mfma_f32_16x16x32_bf16 v[40:43], v[164:167], v[196:199], v[40:43]
	v_mfma_f32_16x16x32_bf16 v[28:31], v[156:159], v[204:207], v[28:31]
	v_mfma_f32_16x16x32_bf16 v[24:27], v[164:167], v[204:207], v[24:27]
	v_mfma_f32_16x16x32_bf16 v[12:15], v[156:159], v[212:215], v[12:15]
	v_mfma_f32_16x16x32_bf16 v[8:11], v[164:167], v[212:215], v[8:11]
	s_setprio 0
	s_setprio 1
	v_mfma_f32_16x16x32_bf16 v[52:55], v[168:171], v[184:187], v[52:55]
	v_mfma_f32_16x16x32_bf16 v[48:51], v[176:179], v[184:187], v[48:51]
	v_mfma_f32_16x16x32_bf16 v[36:39], v[168:171], v[192:195], v[36:39]
	v_mfma_f32_16x16x32_bf16 v[32:35], v[176:179], v[192:195], v[32:35]
	v_mfma_f32_16x16x32_bf16 v[20:23], v[168:171], v[200:203], v[20:23]
	v_mfma_f32_16x16x32_bf16 v[16:19], v[176:179], v[200:203], v[16:19]
	v_mfma_f32_16x16x32_bf16 v[4:7], v[168:171], v[208:211], v[4:7]
	v_mfma_f32_16x16x32_bf16 v[0:3], v[176:179], v[208:211], v[0:3]
	v_mfma_f32_16x16x32_bf16 v[52:55], v[172:175], v[188:191], v[52:55]
	v_mfma_f32_16x16x32_bf16 v[48:51], v[180:183], v[188:191], v[48:51]
	v_mfma_f32_16x16x32_bf16 v[36:39], v[172:175], v[196:199], v[36:39]
	v_mfma_f32_16x16x32_bf16 v[32:35], v[180:183], v[196:199], v[32:35]
	v_mfma_f32_16x16x32_bf16 v[20:23], v[172:175], v[204:207], v[20:23]
	v_mfma_f32_16x16x32_bf16 v[16:19], v[180:183], v[204:207], v[16:19]
	v_mfma_f32_16x16x32_bf16 v[4:7], v[172:175], v[212:215], v[4:7]
	v_mfma_f32_16x16x32_bf16 v[0:3], v[180:183], v[212:215], v[0:3]
	s_setprio 0
	s_add_i32 s46, s46, 2
	s_add_u32 s20, s20, 0x100
	s_addc_u32 s21, s21, 0
	s_cmp_gt_u32 s46, 29
	s_barrier
	s_cbranch_scc0 .LBB0_797
	s_cmpk_lt_u32 s38, 0x100
	s_cbranch_scc0 .LBB0_800
	s_barrier

.LBB0_1058:
	ds_read_b128 v[136:139], v143
	ds_read_b128 v[146:149], v143 offset:1024
	ds_read_b128 v[150:153], v143 offset:2048
	ds_read_b128 v[154:157], v143 offset:3072
	ds_read_b128 v[158:161], v144
	ds_read_b128 v[162:165], v144 offset:1024
	ds_read_b128 v[166:169], v144 offset:2048
	ds_read_b128 v[170:173], v144 offset:3072
	s_add_u32 s26, s24, 0xfffc0080
	s_addc_u32 s27, s25, -1
	s_cmp_eq_u32 s56, 12
	s_cselect_b32 s29, s46, s27
	s_cselect_b32 s28, s47, s26
	s_cselect_b32 s27, s48, s51
	s_cselect_b32 s26, s49, s50
	v_lshl_add_u64 v[206:207], s[24:25], 0, v[132:133]
	s_add_i32 m0, s35, 0xc000
	ds_read_b128 v[174:177], v145
	ds_read_b128 v[178:181], v145 offset:1024
	ds_read_b128 v[182:185], v145 offset:2048
	ds_read_b128 v[186:189], v145 offset:3072
	ds_read_b128 v[190:193], v145 offset:4096
	ds_read_b128 v[194:197], v145 offset:5120
	ds_read_b128 v[198:201], v145 offset:6144
	ds_read_b128 v[202:205], v145 offset:7168
	global_load_lds_dwordx4 v[206:207], off
	v_lshl_add_u64 v[206:207], s[24:25], 0, v[134:135]
	s_add_i32 m0, s35, 0xe000
	s_nop 0
	global_load_lds_dwordx4 v[206:207], off
	s_waitcnt vmcnt(8)
	s_waitcnt lgkmcnt(0)
	s_barrier
	s_setprio 1
	s_waitcnt lgkmcnt(0)
	v_mfma_f32_16x16x32_bf16 v[124:127], v[136:139], v[174:177], v[124:127]
	v_mfma_f32_16x16x32_bf16 v[120:123], v[150:153], v[174:177], v[120:123]
	v_mfma_f32_16x16x32_bf16 v[108:111], v[136:139], v[182:185], v[108:111]
	v_mfma_f32_16x16x32_bf16 v[104:107], v[150:153], v[182:185], v[104:107]
	v_mfma_f32_16x16x32_bf16 v[92:95], v[136:139], v[190:193], v[92:95]
	v_mfma_f32_16x16x32_bf16 v[88:91], v[150:153], v[190:193], v[88:91]
	v_mfma_f32_16x16x32_bf16 v[76:79], v[136:139], v[198:201], v[76:79]
	v_mfma_f32_16x16x32_bf16 v[72:75], v[150:153], v[198:201], v[72:75]
	v_mfma_f32_16x16x32_bf16 v[124:127], v[146:149], v[178:181], v[124:127]
	v_mfma_f32_16x16x32_bf16 v[120:123], v[154:157], v[178:181], v[120:123]
	v_mfma_f32_16x16x32_bf16 v[108:111], v[146:149], v[186:189], v[108:111]
	v_mfma_f32_16x16x32_bf16 v[104:107], v[154:157], v[186:189], v[104:107]
	v_mfma_f32_16x16x32_bf16 v[92:95], v[146:149], v[194:197], v[92:95]
	v_mfma_f32_16x16x32_bf16 v[88:91], v[154:157], v[194:197], v[88:91]
	v_mfma_f32_16x16x32_bf16 v[76:79], v[146:149], v[202:205], v[76:79]
	v_mfma_f32_16x16x32_bf16 v[72:75], v[154:157], v[202:205], v[72:75]
	s_setprio 0
	s_setprio 1
	v_mfma_f32_16x16x32_bf16 v[116:119], v[158:161], v[174:177], v[116:119]
	v_mfma_f32_16x16x32_bf16 v[112:115], v[166:169], v[174:177], v[112:115]
	v_mfma_f32_16x16x32_bf16 v[100:103], v[158:161], v[182:185], v[100:103]
	v_mfma_f32_16x16x32_bf16 v[96:99], v[166:169], v[182:185], v[96:99]
	v_mfma_f32_16x16x32_bf16 v[84:87], v[158:161], v[190:193], v[84:87]
	v_mfma_f32_16x16x32_bf16 v[80:83], v[166:169], v[190:193], v[80:83]
	v_mfma_f32_16x16x32_bf16 v[68:71], v[158:161], v[198:201], v[68:71]
	v_mfma_f32_16x16x32_bf16 v[64:67], v[166:169], v[198:201], v[64:67]
	v_mfma_f32_16x16x32_bf16 v[116:119], v[162:165], v[178:181], v[116:119]
	v_mfma_f32_16x16x32_bf16 v[112:115], v[170:173], v[178:181], v[112:115]
	v_mfma_f32_16x16x32_bf16 v[100:103], v[162:165], v[186:189], v[100:103]
	v_mfma_f32_16x16x32_bf16 v[96:99], v[170:173], v[186:189], v[96:99]
	v_mfma_f32_16x16x32_bf16 v[84:87], v[162:165], v[194:197], v[84:87]
	v_mfma_f32_16x16x32_bf16 v[80:83], v[170:173], v[194:197], v[80:83]
	v_mfma_f32_16x16x32_bf16 v[68:71], v[162:165], v[202:205], v[68:71]
	v_mfma_f32_16x16x32_bf16 v[64:67], v[170:173], v[202:205], v[64:67]
	s_setprio 0
	s_barrier
	s_add_i32 s57, s42, s33
	v_lshl_add_u64 v[206:207], s[26:27], 0, v[130:131]
	s_mov_b32 m0, s57
	ds_read_b128 v[174:177], v145 offset:16384
	ds_read_b128 v[178:181], v145 offset:17408
	ds_read_b128 v[182:185], v145 offset:18432
	ds_read_b128 v[186:189], v145 offset:19456
	ds_read_b128 v[190:193], v145 offset:20480
	ds_read_b128 v[194:197], v145 offset:21504
	ds_read_b128 v[198:201], v145 offset:22528
	ds_read_b128 v[202:205], v145 offset:23552
	global_load_lds_dwordx4 v[206:207], off
	s_add_i32 m0, s57, 0x2000
	s_add_u32 s58, s26, 0x40000
	v_lshl_add_u64 v[208:209], s[26:27], 0, v[128:129]
	s_addc_u32 s59, s27, 0
	s_add_i32 s57, s43, s33
	global_load_lds_dwordx4 v[208:209], off
	v_lshl_add_u64 v[210:211], s[58:59], 0, v[130:131]
	s_mov_b32 m0, s57
	v_lshl_add_u64 v[212:213], s[28:29], 0, v[128:129]
	global_load_lds_dwordx4 v[210:211], off
	v_lshl_add_u64 v[210:211], s[58:59], 0, v[128:129]
	s_add_i32 m0, s57, 0x2000
	s_nop 0
	global_load_lds_dwordx4 v[210:211], off
	v_lshl_add_u64 v[210:211], s[28:29], 0, v[130:131]
	s_mov_b32 m0, s35
	s_nop 0
	global_load_lds_dwordx4 v[210:211], off
	s_mov_b32 m0, s36
	s_nop 0
	global_load_lds_dwordx4 v[212:213], off
	s_waitcnt vmcnt(8)
	s_waitcnt lgkmcnt(0)
	s_barrier
	s_setprio 1
	s_waitcnt lgkmcnt(0)
	v_mfma_f32_16x16x32_bf16 v[60:63], v[136:139], v[174:177], v[60:63]
	v_mfma_f32_16x16x32_bf16 v[56:59], v[150:153], v[174:177], v[56:59]
	v_mfma_f32_16x16x32_bf16 v[44:47], v[136:139], v[182:185], v[44:47]
	v_mfma_f32_16x16x32_bf16 v[40:43], v[150:153], v[182:185], v[40:43]
	v_mfma_f32_16x16x32_bf16 v[28:31], v[136:139], v[190:193], v[28:31]
	v_mfma_f32_16x16x32_bf16 v[24:27], v[150:153], v[190:193], v[24:27]
	v_mfma_f32_16x16x32_bf16 v[12:15], v[136:139], v[198:201], v[12:15]
	v_mfma_f32_16x16x32_bf16 v[8:11], v[150:153], v[198:201], v[8:11]
	v_mfma_f32_16x16x32_bf16 v[60:63], v[146:149], v[178:181], v[60:63]
	v_mfma_f32_16x16x32_bf16 v[56:59], v[154:157], v[178:181], v[56:59]
	v_mfma_f32_16x16x32_bf16 v[44:47], v[146:149], v[186:189], v[44:47]
	v_mfma_f32_16x16x32_bf16 v[40:43], v[154:157], v[186:189], v[40:43]
	v_mfma_f32_16x16x32_bf16 v[28:31], v[146:149], v[194:197], v[28:31]
	v_mfma_f32_16x16x32_bf16 v[24:27], v[154:157], v[194:197], v[24:27]
	v_mfma_f32_16x16x32_bf16 v[12:15], v[146:149], v[202:205], v[12:15]
	v_mfma_f32_16x16x32_bf16 v[8:11], v[154:157], v[202:205], v[8:11]
	s_setprio 0
	s_setprio 1
	v_mfma_f32_16x16x32_bf16 v[52:55], v[158:161], v[174:177], v[52:55]
	v_mfma_f32_16x16x32_bf16 v[48:51], v[166:169], v[174:177], v[48:51]
	v_mfma_f32_16x16x32_bf16 v[36:39], v[158:161], v[182:185], v[36:39]
	v_mfma_f32_16x16x32_bf16 v[32:35], v[166:169], v[182:185], v[32:35]
	v_mfma_f32_16x16x32_bf16 v[20:23], v[158:161], v[190:193], v[20:23]
	v_mfma_f32_16x16x32_bf16 v[16:19], v[166:169], v[190:193], v[16:19]
	v_mfma_f32_16x16x32_bf16 v[4:7], v[158:161], v[198:201], v[4:7]
	v_mfma_f32_16x16x32_bf16 v[0:3], v[166:169], v[198:201], v[0:3]
	v_mfma_f32_16x16x32_bf16 v[52:55], v[162:165], v[178:181], v[52:55]
	v_mfma_f32_16x16x32_bf16 v[48:51], v[170:173], v[178:181], v[48:51]
	v_mfma_f32_16x16x32_bf16 v[36:39], v[162:165], v[186:189], v[36:39]
	v_mfma_f32_16x16x32_bf16 v[32:35], v[170:173], v[186:189], v[32:35]
	v_mfma_f32_16x16x32_bf16 v[20:23], v[162:165], v[194:197], v[20:23]
	v_mfma_f32_16x16x32_bf16 v[16:19], v[170:173], v[194:197], v[16:19]
	v_mfma_f32_16x16x32_bf16 v[4:7], v[162:165], v[202:205], v[4:7]
	v_mfma_f32_16x16x32_bf16 v[0:3], v[170:173], v[202:205], v[0:3]
	s_setprio 0
	s_barrier
	s_add_i32 s57, 0, 0x18000
	s_add_i32 s58, 0, 0x1c000
	v_add_u32_e32 v154, s57, v141
	v_add_u32_e32 v170, s58, v141
	ds_read_b128 v[136:139], v154
	ds_read_b128 v[146:149], v154 offset:1024
	ds_read_b128 v[150:153], v154 offset:2048
	ds_read_b128 v[154:157], v154 offset:3072
	ds_read_b128 v[158:161], v170
	ds_read_b128 v[162:165], v170 offset:1024
	ds_read_b128 v[166:169], v170 offset:2048
	ds_read_b128 v[170:173], v170 offset:3072
	s_add_u32 s28, s28, 0x40000
	s_addc_u32 s29, s29, 0
	s_mov_b32 m0, s37
	v_lshl_add_u64 v[214:215], s[28:29], 0, v[130:131]
	ds_read_b128 v[174:177], v145 offset:32768
	ds_read_b128 v[178:181], v145 offset:33792
	ds_read_b128 v[182:185], v145 offset:34816
	ds_read_b128 v[186:189], v145 offset:35840
	ds_read_b128 v[190:193], v145 offset:36864
	ds_read_b128 v[194:197], v145 offset:37888
	ds_read_b128 v[198:201], v145 offset:38912
	ds_read_b128 v[202:205], v145 offset:39936
	global_load_lds_dwordx4 v[214:215], off
	v_lshl_add_u64 v[214:215], s[28:29], 0, v[128:129]
	s_mov_b32 m0, s38
	s_nop 0
	global_load_lds_dwordx4 v[214:215], off
	s_waitcnt vmcnt(8)
	s_waitcnt lgkmcnt(0)
	s_barrier
	s_setprio 1
	s_waitcnt lgkmcnt(0)
	v_mfma_f32_16x16x32_bf16 v[124:127], v[136:139], v[174:177], v[124:127]
	v_mfma_f32_16x16x32_bf16 v[120:123], v[150:153], v[174:177], v[120:123]
	v_mfma_f32_16x16x32_bf16 v[108:111], v[136:139], v[182:185], v[108:111]
	v_mfma_f32_16x16x32_bf16 v[104:107], v[150:153], v[182:185], v[104:107]
	v_mfma_f32_16x16x32_bf16 v[92:95], v[136:139], v[190:193], v[92:95]
	v_mfma_f32_16x16x32_bf16 v[88:91], v[150:153], v[190:193], v[88:91]
	v_mfma_f32_16x16x32_bf16 v[76:79], v[136:139], v[198:201], v[76:79]
	v_mfma_f32_16x16x32_bf16 v[72:75], v[150:153], v[198:201], v[72:75]
	v_mfma_f32_16x16x32_bf16 v[124:127], v[146:149], v[178:181], v[124:127]
	v_mfma_f32_16x16x32_bf16 v[120:123], v[154:157], v[178:181], v[120:123]
	v_mfma_f32_16x16x32_bf16 v[108:111], v[146:149], v[186:189], v[108:111]
	v_mfma_f32_16x16x32_bf16 v[104:107], v[154:157], v[186:189], v[104:107]
	v_mfma_f32_16x16x32_bf16 v[92:95], v[146:149], v[194:197], v[92:95]
	v_mfma_f32_16x16x32_bf16 v[88:91], v[154:157], v[194:197], v[88:91]
	v_mfma_f32_16x16x32_bf16 v[76:79], v[146:149], v[202:205], v[76:79]
	v_mfma_f32_16x16x32_bf16 v[72:75], v[154:157], v[202:205], v[72:75]
	s_setprio 0
	s_setprio 1
	v_mfma_f32_16x16x32_bf16 v[116:119], v[158:161], v[174:177], v[116:119]
	v_mfma_f32_16x16x32_bf16 v[112:115], v[166:169], v[174:177], v[112:115]
	v_mfma_f32_16x16x32_bf16 v[100:103], v[158:161], v[182:185], v[100:103]
	v_mfma_f32_16x16x32_bf16 v[96:99], v[166:169], v[182:185], v[96:99]
	v_mfma_f32_16x16x32_bf16 v[84:87], v[158:161], v[190:193], v[84:87]
	v_mfma_f32_16x16x32_bf16 v[80:83], v[166:169], v[190:193], v[80:83]
	v_mfma_f32_16x16x32_bf16 v[68:71], v[158:161], v[198:201], v[68:71]
	v_mfma_f32_16x16x32_bf16 v[64:67], v[166:169], v[198:201], v[64:67]
	v_mfma_f32_16x16x32_bf16 v[116:119], v[162:165], v[178:181], v[116:119]
	v_mfma_f32_16x16x32_bf16 v[112:115], v[170:173], v[178:181], v[112:115]
	v_mfma_f32_16x16x32_bf16 v[100:103], v[162:165], v[186:189], v[100:103]
	v_mfma_f32_16x16x32_bf16 v[96:99], v[170:173], v[186:189], v[96:99]
	v_mfma_f32_16x16x32_bf16 v[84:87], v[162:165], v[194:197], v[84:87]
	v_mfma_f32_16x16x32_bf16 v[80:83], v[170:173], v[194:197], v[80:83]
	v_mfma_f32_16x16x32_bf16 v[68:71], v[162:165], v[202:205], v[68:71]
	v_mfma_f32_16x16x32_bf16 v[64:67], v[170:173], v[202:205], v[64:67]
	s_setprio 0
	s_barrier
	s_add_i32 s28, s57, s33
	v_lshl_add_u64 v[206:207], v[206:207], 0, s[18:19]
	s_mov_b32 m0, s28
	ds_read_b128 v[174:177], v145 offset:49152
	ds_read_b128 v[178:181], v145 offset:50176
	ds_read_b128 v[182:185], v145 offset:51200
	ds_read_b128 v[186:189], v145 offset:52224
	ds_read_b128 v[190:193], v145 offset:53248
	ds_read_b128 v[194:197], v145 offset:54272
	ds_read_b128 v[198:201], v145 offset:55296
	ds_read_b128 v[202:205], v145 offset:56320
	global_load_lds_dwordx4 v[206:207], off
	s_add_i32 m0, s28, 0x2000
	s_add_u32 s26, s26, 0x40080
	v_lshl_add_u64 v[206:207], v[208:209], 0, s[18:19]
	s_addc_u32 s27, s27, 0
	s_add_i32 s28, s58, s33
	global_load_lds_dwordx4 v[206:207], off
	v_lshl_add_u64 v[206:207], s[26:27], 0, v[130:131]
	s_mov_b32 m0, s28
	s_nop 0
	global_load_lds_dwordx4 v[206:207], off
	v_lshl_add_u64 v[206:207], s[26:27], 0, v[128:129]
	s_add_i32 m0, s28, 0x2000
	s_nop 0
	global_load_lds_dwordx4 v[206:207], off
	v_lshl_add_u64 v[206:207], v[210:211], 0, s[18:19]
	s_mov_b32 m0, s39
	s_nop 0
	global_load_lds_dwordx4 v[206:207], off
	v_lshl_add_u64 v[206:207], v[212:213], 0, s[18:19]
	s_mov_b32 m0, s40
	s_nop 0
	global_load_lds_dwordx4 v[206:207], off
	s_waitcnt vmcnt(8)
	s_waitcnt lgkmcnt(0)
	s_barrier
	s_setprio 1
	s_waitcnt lgkmcnt(0)
	v_mfma_f32_16x16x32_bf16 v[60:63], v[136:139], v[174:177], v[60:63]
	v_mfma_f32_16x16x32_bf16 v[56:59], v[150:153], v[174:177], v[56:59]
	v_mfma_f32_16x16x32_bf16 v[44:47], v[136:139], v[182:185], v[44:47]
	v_mfma_f32_16x16x32_bf16 v[40:43], v[150:153], v[182:185], v[40:43]
	v_mfma_f32_16x16x32_bf16 v[28:31], v[136:139], v[190:193], v[28:31]
	v_mfma_f32_16x16x32_bf16 v[24:27], v[150:153], v[190:193], v[24:27]
	v_mfma_f32_16x16x32_bf16 v[12:15], v[136:139], v[198:201], v[12:15]
	v_mfma_f32_16x16x32_bf16 v[8:11], v[150:153], v[198:201], v[8:11]
	v_mfma_f32_16x16x32_bf16 v[60:63], v[146:149], v[178:181], v[60:63]
	v_mfma_f32_16x16x32_bf16 v[56:59], v[154:157], v[178:181], v[56:59]
	v_mfma_f32_16x16x32_bf16 v[44:47], v[146:149], v[186:189], v[44:47]
	v_mfma_f32_16x16x32_bf16 v[40:43], v[154:157], v[186:189], v[40:43]
	v_mfma_f32_16x16x32_bf16 v[28:31], v[146:149], v[194:197], v[28:31]
	v_mfma_f32_16x16x32_bf16 v[24:27], v[154:157], v[194:197], v[24:27]
	v_mfma_f32_16x16x32_bf16 v[12:15], v[146:149], v[202:205], v[12:15]
	v_mfma_f32_16x16x32_bf16 v[8:11], v[154:157], v[202:205], v[8:11]
	s_setprio 0
	s_setprio 1
	v_mfma_f32_16x16x32_bf16 v[52:55], v[158:161], v[174:177], v[52:55]
	v_mfma_f32_16x16x32_bf16 v[48:51], v[166:169], v[174:177], v[48:51]
	v_mfma_f32_16x16x32_bf16 v[36:39], v[158:161], v[182:185], v[36:39]
	v_mfma_f32_16x16x32_bf16 v[32:35], v[166:169], v[182:185], v[32:35]
	v_mfma_f32_16x16x32_bf16 v[20:23], v[158:161], v[190:193], v[20:23]
	v_mfma_f32_16x16x32_bf16 v[16:19], v[166:169], v[190:193], v[16:19]
	v_mfma_f32_16x16x32_bf16 v[4:7], v[158:161], v[198:201], v[4:7]
	v_mfma_f32_16x16x32_bf16 v[0:3], v[166:169], v[198:201], v[0:3]
	v_mfma_f32_16x16x32_bf16 v[52:55], v[162:165], v[178:181], v[52:55]
	v_mfma_f32_16x16x32_bf16 v[48:51], v[170:173], v[178:181], v[48:51]
	v_mfma_f32_16x16x32_bf16 v[36:39], v[162:165], v[186:189], v[36:39]
	v_mfma_f32_16x16x32_bf16 v[32:35], v[170:173], v[186:189], v[32:35]
	v_mfma_f32_16x16x32_bf16 v[20:23], v[162:165], v[194:197], v[20:23]
	v_mfma_f32_16x16x32_bf16 v[16:19], v[170:173], v[194:197], v[16:19]
	v_mfma_f32_16x16x32_bf16 v[4:7], v[162:165], v[202:205], v[4:7]
	v_mfma_f32_16x16x32_bf16 v[0:3], v[170:173], v[202:205], v[0:3]
	s_setprio 0
	s_add_i32 s56, s56, 2
	s_add_u32 s24, s24, 0x100
	s_addc_u32 s25, s25, 0
	s_add_u32 s50, s50, 0x100
	s_addc_u32 s51, s51, 0
	s_cmp_gt_u32 s56, 13
	s_barrier
	s_cbranch_scc0 .LBB0_1058
	s_and_b64 vcc, exec, s[20:21]
	s_cbranch_vccz .LBB0_1061
	s_barrier

.LBB0_1131:
	s_add_i32 s77, s77, 2
	s_add_u32 s34, s34, 0x100
	s_addc_u32 s35, s35, 0
	s_add_u32 s18, s18, 0x100
	s_addc_u32 s41, s41, 0
	s_cmp_gt_u32 s77, 13
	s_barrier
	s_cbranch_scc1 .LBB0_1140

.LBB0_1282:
	s_add_i32 s84, s84, 2
	s_add_u32 s38, s38, 0x100
	s_addc_u32 s39, s39, 0
	s_add_u32 s16, s16, 0x100
	s_addc_u32 s27, s27, 0
	s_cmp_gt_u32 s84, 29
	s_barrier
	s_cbranch_scc1 .LBB0_1291

.LBB0_1391:
	ds_read_b128 v[24:27], v234
	ds_read_b128 v[28:31], v234 offset:1024
	ds_read_b128 v[96:99], v234 offset:2048
	ds_read_b128 v[100:103], v234 offset:3072
	ds_read_b128 v[144:147], v235
	ds_read_b128 v[148:151], v235 offset:1024
	ds_read_b128 v[152:155], v235 offset:2048
	ds_read_b128 v[156:159], v235 offset:3072
	s_add_u32 s16, s14, 0xfff80080
	s_addc_u32 s17, s15, -1
	s_cmp_eq_u32 s22, 28
	s_cselect_b32 s19, s9, s17
	s_cselect_b32 s18, s13, s16
	s_cselect_b32 s17, s79, s21
	s_cselect_b32 s16, s78, s20
	v_lshl_add_u64 v[204:205], s[14:15], 0, v[192:193]
	s_add_i32 m0, s49, 0xc000
	ds_read_b128 v[160:163], v236
	ds_read_b128 v[164:167], v236 offset:1024
	ds_read_b128 v[168:171], v236 offset:2048
	ds_read_b128 v[172:175], v236 offset:3072
	ds_read_b128 v[176:179], v236 offset:4096
	ds_read_b128 v[180:183], v236 offset:5120
	ds_read_b128 v[196:199], v236 offset:6144
	ds_read_b128 v[200:203], v236 offset:7168
	global_load_lds_dwordx4 v[204:205], off
	v_lshl_add_u64 v[204:205], s[14:15], 0, v[194:195]
	s_add_i32 m0, s49, 0xe000
	s_nop 0
	global_load_lds_dwordx4 v[204:205], off
	s_waitcnt vmcnt(8)
	s_waitcnt lgkmcnt(0)
	s_barrier
	s_setprio 1
	s_waitcnt lgkmcnt(0)
	v_mfma_f32_16x16x32_bf16 v[140:143], v[24:27], v[160:163], v[140:143]
	v_mfma_f32_16x16x32_bf16 v[84:87], v[96:99], v[160:163], v[84:87]
	v_mfma_f32_16x16x32_bf16 v[116:119], v[24:27], v[168:171], v[116:119]
	v_mfma_f32_16x16x32_bf16 v[44:47], v[96:99], v[168:171], v[44:47]
	v_mfma_f32_16x16x32_bf16 v[108:111], v[24:27], v[176:179], v[108:111]
	v_mfma_f32_16x16x32_bf16 v[36:39], v[96:99], v[176:179], v[36:39]
	v_mfma_f32_16x16x32_bf16 v[136:139], v[24:27], v[196:199], v[136:139]
	v_mfma_f32_16x16x32_bf16 v[56:59], v[96:99], v[196:199], v[56:59]
	v_mfma_f32_16x16x32_bf16 v[140:143], v[28:31], v[164:167], v[140:143]
	v_mfma_f32_16x16x32_bf16 v[84:87], v[100:103], v[164:167], v[84:87]
	v_mfma_f32_16x16x32_bf16 v[116:119], v[28:31], v[172:175], v[116:119]
	v_mfma_f32_16x16x32_bf16 v[44:47], v[100:103], v[172:175], v[44:47]
	v_mfma_f32_16x16x32_bf16 v[108:111], v[28:31], v[180:183], v[108:111]
	v_mfma_f32_16x16x32_bf16 v[36:39], v[100:103], v[180:183], v[36:39]
	v_mfma_f32_16x16x32_bf16 v[136:139], v[28:31], v[200:203], v[136:139]
	v_mfma_f32_16x16x32_bf16 v[56:59], v[100:103], v[200:203], v[56:59]
	s_setprio 0
	s_setprio 1
	v_mfma_f32_16x16x32_bf16 v[128:131], v[144:147], v[160:163], v[128:131]
	v_mfma_f32_16x16x32_bf16 v[80:83], v[152:155], v[160:163], v[80:83]
	v_mfma_f32_16x16x32_bf16 v[112:115], v[144:147], v[168:171], v[112:115]
	v_mfma_f32_16x16x32_bf16 v[40:43], v[152:155], v[168:171], v[40:43]
	v_mfma_f32_16x16x32_bf16 v[104:107], v[144:147], v[176:179], v[104:107]
	v_mfma_f32_16x16x32_bf16 v[32:35], v[152:155], v[176:179], v[32:35]
	v_mfma_f32_16x16x32_bf16 v[132:135], v[144:147], v[196:199], v[132:135]
	v_mfma_f32_16x16x32_bf16 v[60:63], v[152:155], v[196:199], v[60:63]
	v_mfma_f32_16x16x32_bf16 v[128:131], v[148:151], v[164:167], v[128:131]
	v_mfma_f32_16x16x32_bf16 v[80:83], v[156:159], v[164:167], v[80:83]
	v_mfma_f32_16x16x32_bf16 v[112:115], v[148:151], v[172:175], v[112:115]
	v_mfma_f32_16x16x32_bf16 v[40:43], v[156:159], v[172:175], v[40:43]
	v_mfma_f32_16x16x32_bf16 v[104:107], v[148:151], v[180:183], v[104:107]
	v_mfma_f32_16x16x32_bf16 v[32:35], v[156:159], v[180:183], v[32:35]
	v_mfma_f32_16x16x32_bf16 v[132:135], v[148:151], v[200:203], v[132:135]
	v_mfma_f32_16x16x32_bf16 v[60:63], v[156:159], v[200:203], v[60:63]
	s_setprio 0
	s_barrier
	s_add_i32 s23, s45, s51
	v_lshl_add_u64 v[204:205], s[16:17], 0, v[188:189]
	s_mov_b32 m0, s23
	ds_read_b128 v[160:163], v236 offset:16384
	ds_read_b128 v[164:167], v236 offset:17408
	ds_read_b128 v[168:171], v236 offset:18432
	ds_read_b128 v[172:175], v236 offset:19456
	ds_read_b128 v[176:179], v236 offset:20480
	ds_read_b128 v[180:183], v236 offset:21504
	ds_read_b128 v[196:199], v236 offset:22528
	ds_read_b128 v[200:203], v236 offset:23552
	global_load_lds_dwordx4 v[204:205], off
	s_add_i32 m0, s23, 0x2000
	s_add_u32 s24, s16, 0x84000
	v_lshl_add_u64 v[206:207], s[16:17], 0, v[184:185]
	s_addc_u32 s25, s17, 0
	s_add_i32 s23, s48, s51
	global_load_lds_dwordx4 v[206:207], off
	v_lshl_add_u64 v[208:209], s[24:25], 0, v[188:189]
	s_mov_b32 m0, s23
	v_lshl_add_u64 v[210:211], s[18:19], 0, v[186:187]
	global_load_lds_dwordx4 v[208:209], off
	v_lshl_add_u64 v[208:209], s[24:25], 0, v[184:185]
	s_add_i32 m0, s23, 0x2000
	s_nop 0
	global_load_lds_dwordx4 v[208:209], off
	v_lshl_add_u64 v[208:209], s[18:19], 0, v[190:191]
	s_mov_b32 m0, s49
	s_nop 0
	global_load_lds_dwordx4 v[208:209], off
	s_mov_b32 m0, s50
	s_nop 0
	global_load_lds_dwordx4 v[210:211], off
	s_waitcnt vmcnt(8)
	s_waitcnt lgkmcnt(0)
	s_barrier
	s_setprio 1
	s_waitcnt lgkmcnt(0)
	v_mfma_f32_16x16x32_bf16 v[124:127], v[24:27], v[160:163], v[124:127]
	v_mfma_f32_16x16x32_bf16 v[52:55], v[96:99], v[160:163], v[52:55]
	v_mfma_f32_16x16x32_bf16 v[76:79], v[24:27], v[168:171], v[76:79]
	v_mfma_f32_16x16x32_bf16 v[12:15], v[96:99], v[168:171], v[12:15]
	v_mfma_f32_16x16x32_bf16 v[68:71], v[24:27], v[176:179], v[68:71]
	v_mfma_f32_16x16x32_bf16 v[4:7], v[96:99], v[176:179], v[4:7]
	v_mfma_f32_16x16x32_bf16 v[16:19], v[96:99], v[196:199], v[16:19]
	v_mfma_f32_16x16x32_bf16 v[124:127], v[28:31], v[164:167], v[124:127]
	v_mfma_f32_16x16x32_bf16 v[52:55], v[100:103], v[164:167], v[52:55]
	v_mfma_f32_16x16x32_bf16 v[76:79], v[28:31], v[172:175], v[76:79]
	v_mfma_f32_16x16x32_bf16 v[12:15], v[100:103], v[172:175], v[12:15]
	v_mfma_f32_16x16x32_bf16 v[68:71], v[28:31], v[180:183], v[68:71]
	v_mfma_f32_16x16x32_bf16 v[4:7], v[100:103], v[180:183], v[4:7]
	v_mfma_f32_16x16x32_bf16 v[24:27], v[24:27], v[196:199], v[88:91]
	v_mfma_f32_16x16x32_bf16 v[16:19], v[100:103], v[200:203], v[16:19]
	v_mfma_f32_16x16x32_bf16 v[24:27], v[28:31], v[200:203], v[24:27]
	s_setprio 0
	s_setprio 1
	v_mfma_f32_16x16x32_bf16 v[48:51], v[152:155], v[160:163], v[48:51]
	v_mfma_f32_16x16x32_bf16 v[72:75], v[144:147], v[168:171], v[72:75]
	v_mfma_f32_16x16x32_bf16 v[8:11], v[152:155], v[168:171], v[8:11]
	v_mfma_f32_16x16x32_bf16 v[64:67], v[144:147], v[176:179], v[64:67]
	v_mfma_f32_16x16x32_bf16 v[0:3], v[152:155], v[176:179], v[0:3]
	v_mfma_f32_16x16x32_bf16 v[88:91], v[144:147], v[196:199], v[92:95]
	v_mfma_f32_16x16x32_bf16 v[20:23], v[152:155], v[196:199], v[20:23]
	v_mfma_f32_16x16x32_bf16 v[28:31], v[144:147], v[160:163], v[120:123]
	v_mfma_f32_16x16x32_bf16 v[48:51], v[156:159], v[164:167], v[48:51]
	v_mfma_f32_16x16x32_bf16 v[72:75], v[148:151], v[172:175], v[72:75]
	v_mfma_f32_16x16x32_bf16 v[8:11], v[156:159], v[172:175], v[8:11]
	v_mfma_f32_16x16x32_bf16 v[64:67], v[148:151], v[180:183], v[64:67]
	v_mfma_f32_16x16x32_bf16 v[0:3], v[156:159], v[180:183], v[0:3]
	v_mfma_f32_16x16x32_bf16 v[92:95], v[148:151], v[200:203], v[88:91]
	v_mfma_f32_16x16x32_bf16 v[20:23], v[156:159], v[200:203], v[20:23]
	v_mfma_f32_16x16x32_bf16 v[28:31], v[148:151], v[164:167], v[28:31]
	s_setprio 0
	s_barrier
	s_add_i32 s23, 0, 0x18000
	s_add_i32 s24, 0, 0x1c000
	v_add_u32_e32 v120, s23, v222
	v_add_u32_e32 v156, s24, v222
	ds_read_b128 v[88:91], v120
	ds_read_b128 v[96:99], v120 offset:1024
	ds_read_b128 v[100:103], v120 offset:2048
	ds_read_b128 v[120:123], v120 offset:3072
	ds_read_b128 v[144:147], v156
	ds_read_b128 v[148:151], v156 offset:1024
	ds_read_b128 v[152:155], v156 offset:2048
	ds_read_b128 v[156:159], v156 offset:3072
	s_add_u32 s18, s18, 0x80000
	s_addc_u32 s19, s19, 0
	s_mov_b32 m0, s33
	v_lshl_add_u64 v[212:213], s[18:19], 0, v[190:191]
	ds_read_b128 v[160:163], v236 offset:32768
	ds_read_b128 v[164:167], v236 offset:33792
	ds_read_b128 v[168:171], v236 offset:34816
	ds_read_b128 v[172:175], v236 offset:35840
	ds_read_b128 v[176:179], v236 offset:36864
	ds_read_b128 v[180:183], v236 offset:37888
	ds_read_b128 v[196:199], v236 offset:38912
	ds_read_b128 v[200:203], v236 offset:39936
	global_load_lds_dwordx4 v[212:213], off
	v_lshl_add_u64 v[212:213], s[18:19], 0, v[186:187]
	s_mov_b32 m0, s30
	s_nop 0
	global_load_lds_dwordx4 v[212:213], off
	s_waitcnt vmcnt(8)
	s_waitcnt lgkmcnt(0)
	s_barrier
	s_setprio 1
	s_waitcnt lgkmcnt(0)
	v_mfma_f32_16x16x32_bf16 v[140:143], v[88:91], v[160:163], v[140:143]
	v_mfma_f32_16x16x32_bf16 v[84:87], v[100:103], v[160:163], v[84:87]
	v_mfma_f32_16x16x32_bf16 v[116:119], v[88:91], v[168:171], v[116:119]
	v_mfma_f32_16x16x32_bf16 v[44:47], v[100:103], v[168:171], v[44:47]
	v_mfma_f32_16x16x32_bf16 v[108:111], v[88:91], v[176:179], v[108:111]
	v_mfma_f32_16x16x32_bf16 v[36:39], v[100:103], v[176:179], v[36:39]
	v_mfma_f32_16x16x32_bf16 v[136:139], v[88:91], v[196:199], v[136:139]
	v_mfma_f32_16x16x32_bf16 v[56:59], v[100:103], v[196:199], v[56:59]
	v_mfma_f32_16x16x32_bf16 v[140:143], v[96:99], v[164:167], v[140:143]
	v_mfma_f32_16x16x32_bf16 v[84:87], v[120:123], v[164:167], v[84:87]
	v_mfma_f32_16x16x32_bf16 v[116:119], v[96:99], v[172:175], v[116:119]
	v_mfma_f32_16x16x32_bf16 v[44:47], v[120:123], v[172:175], v[44:47]
	v_mfma_f32_16x16x32_bf16 v[108:111], v[96:99], v[180:183], v[108:111]
	v_mfma_f32_16x16x32_bf16 v[36:39], v[120:123], v[180:183], v[36:39]
	v_mfma_f32_16x16x32_bf16 v[136:139], v[96:99], v[200:203], v[136:139]
	v_mfma_f32_16x16x32_bf16 v[56:59], v[120:123], v[200:203], v[56:59]
	s_setprio 0
	s_setprio 1
	v_mfma_f32_16x16x32_bf16 v[128:131], v[144:147], v[160:163], v[128:131]
	v_mfma_f32_16x16x32_bf16 v[80:83], v[152:155], v[160:163], v[80:83]
	v_mfma_f32_16x16x32_bf16 v[112:115], v[144:147], v[168:171], v[112:115]
	v_mfma_f32_16x16x32_bf16 v[40:43], v[152:155], v[168:171], v[40:43]
	v_mfma_f32_16x16x32_bf16 v[104:107], v[144:147], v[176:179], v[104:107]
	v_mfma_f32_16x16x32_bf16 v[32:35], v[152:155], v[176:179], v[32:35]
	v_mfma_f32_16x16x32_bf16 v[132:135], v[144:147], v[196:199], v[132:135]
	v_mfma_f32_16x16x32_bf16 v[60:63], v[152:155], v[196:199], v[60:63]
	v_mfma_f32_16x16x32_bf16 v[128:131], v[148:151], v[164:167], v[128:131]
	v_mfma_f32_16x16x32_bf16 v[80:83], v[156:159], v[164:167], v[80:83]
	v_mfma_f32_16x16x32_bf16 v[112:115], v[148:151], v[172:175], v[112:115]
	v_mfma_f32_16x16x32_bf16 v[40:43], v[156:159], v[172:175], v[40:43]
	v_mfma_f32_16x16x32_bf16 v[104:107], v[148:151], v[180:183], v[104:107]
	v_mfma_f32_16x16x32_bf16 v[32:35], v[156:159], v[180:183], v[32:35]
	v_mfma_f32_16x16x32_bf16 v[132:135], v[148:151], v[200:203], v[132:135]
	v_mfma_f32_16x16x32_bf16 v[60:63], v[156:159], v[200:203], v[60:63]
	s_setprio 0
	s_barrier
	s_add_i32 s18, s23, s51
	v_lshl_add_u64 v[204:205], v[204:205], 0, s[58:59]
	s_mov_b32 m0, s18
	ds_read_b128 v[160:163], v236 offset:49152
	ds_read_b128 v[164:167], v236 offset:50176
	ds_read_b128 v[168:171], v236 offset:51200
	ds_read_b128 v[172:175], v236 offset:52224
	ds_read_b128 v[176:179], v236 offset:53248
	ds_read_b128 v[180:183], v236 offset:54272
	ds_read_b128 v[196:199], v236 offset:55296
	ds_read_b128 v[200:203], v236 offset:56320
	global_load_lds_dwordx4 v[204:205], off
	s_add_i32 m0, s18, 0x2000
	s_add_u32 s16, s16, 0x84080
	v_lshl_add_u64 v[204:205], v[206:207], 0, s[58:59]
	s_addc_u32 s17, s17, 0
	s_add_i32 s18, s24, s51
	global_load_lds_dwordx4 v[204:205], off
	v_lshl_add_u64 v[204:205], s[16:17], 0, v[188:189]
	s_mov_b32 m0, s18
	s_nop 0
	global_load_lds_dwordx4 v[204:205], off
	v_lshl_add_u64 v[204:205], s[16:17], 0, v[184:185]
	s_add_i32 m0, s18, 0x2000
	s_nop 0
	global_load_lds_dwordx4 v[204:205], off
	v_lshl_add_u64 v[204:205], v[208:209], 0, s[58:59]
	s_mov_b32 m0, s31
	s_nop 0
	global_load_lds_dwordx4 v[204:205], off
	v_lshl_add_u64 v[204:205], v[210:211], 0, s[58:59]
	s_mov_b32 m0, s38
	s_nop 0
	global_load_lds_dwordx4 v[204:205], off
	s_waitcnt vmcnt(8)
	s_waitcnt lgkmcnt(0)
	s_barrier
	s_setprio 1
	s_waitcnt lgkmcnt(0)
	v_mfma_f32_16x16x32_bf16 v[124:127], v[88:91], v[160:163], v[124:127]
	v_mfma_f32_16x16x32_bf16 v[52:55], v[100:103], v[160:163], v[52:55]
	v_mfma_f32_16x16x32_bf16 v[76:79], v[88:91], v[168:171], v[76:79]
	v_mfma_f32_16x16x32_bf16 v[12:15], v[100:103], v[168:171], v[12:15]
	v_mfma_f32_16x16x32_bf16 v[68:71], v[88:91], v[176:179], v[68:71]
	v_mfma_f32_16x16x32_bf16 v[4:7], v[100:103], v[176:179], v[4:7]
	v_mfma_f32_16x16x32_bf16 v[24:27], v[88:91], v[196:199], v[24:27]
	v_mfma_f32_16x16x32_bf16 v[16:19], v[100:103], v[196:199], v[16:19]
	v_mfma_f32_16x16x32_bf16 v[124:127], v[96:99], v[164:167], v[124:127]
	v_mfma_f32_16x16x32_bf16 v[52:55], v[120:123], v[164:167], v[52:55]
	v_mfma_f32_16x16x32_bf16 v[76:79], v[96:99], v[172:175], v[76:79]
	v_mfma_f32_16x16x32_bf16 v[12:15], v[120:123], v[172:175], v[12:15]
	v_mfma_f32_16x16x32_bf16 v[68:71], v[96:99], v[180:183], v[68:71]
	v_mfma_f32_16x16x32_bf16 v[4:7], v[120:123], v[180:183], v[4:7]
	v_mfma_f32_16x16x32_bf16 v[88:91], v[96:99], v[200:203], v[24:27]
	v_mfma_f32_16x16x32_bf16 v[16:19], v[120:123], v[200:203], v[16:19]
	s_setprio 0
	s_setprio 1
	v_mfma_f32_16x16x32_bf16 v[24:27], v[144:147], v[160:163], v[28:31]
	v_mfma_f32_16x16x32_bf16 v[120:123], v[148:151], v[164:167], v[24:27]
	v_mfma_f32_16x16x32_bf16 v[24:27], v[152:155], v[160:163], v[48:51]
	v_mfma_f32_16x16x32_bf16 v[48:51], v[156:159], v[164:167], v[24:27]
	v_mfma_f32_16x16x32_bf16 v[24:27], v[144:147], v[168:171], v[72:75]
	v_mfma_f32_16x16x32_bf16 v[72:75], v[148:151], v[172:175], v[24:27]
	v_mfma_f32_16x16x32_bf16 v[24:27], v[144:147], v[176:179], v[64:67]
	v_mfma_f32_16x16x32_bf16 v[8:11], v[152:155], v[168:171], v[8:11]
	v_mfma_f32_16x16x32_bf16 v[64:67], v[148:151], v[180:183], v[24:27]
	v_mfma_f32_16x16x32_bf16 v[0:3], v[152:155], v[176:179], v[0:3]
	v_mfma_f32_16x16x32_bf16 v[24:27], v[144:147], v[196:199], v[92:95]
	v_mfma_f32_16x16x32_bf16 v[20:23], v[152:155], v[196:199], v[20:23]
	v_mfma_f32_16x16x32_bf16 v[8:11], v[156:159], v[172:175], v[8:11]
	v_mfma_f32_16x16x32_bf16 v[0:3], v[156:159], v[180:183], v[0:3]
	v_mfma_f32_16x16x32_bf16 v[92:95], v[148:151], v[200:203], v[24:27]
	v_mfma_f32_16x16x32_bf16 v[20:23], v[156:159], v[200:203], v[20:23]
	s_setprio 0
	s_add_i32 s22, s22, 2
	s_add_u32 s14, s14, 0x100
	s_addc_u32 s15, s15, 0
	s_add_u32 s20, s20, 0x100
	s_addc_u32 s21, s21, 0
	s_cmp_gt_u32 s22, 29
	s_barrier
	s_cbranch_scc0 .LBB0_1391
	s_and_b64 vcc, exec, s[82:83]
	s_cbranch_vccz .LBB0_1394
	s_barrier
